# P5 GLA chunk outputs: gate rows of a unit requested at the start of its MFMA section instead of one load per row behind the previous row's store; per-row vmcnt(0) drains removed; gla_norm_g pointer re
# baseline (speedup 1.0000x reference)
; #define LAS __attribute__((address_space(3)))
; __device__ __forceinline__ int crow(int r, int hi) { return (r & 3) + 8 * (r >> 2) + 4 * hi; }
; __device__ __forceinline__ int crow(int r, int hi) { return (r & 3) + 8 * (r >> 2) + 4 * hi; }
; __device__ __forceinline__ unsigned short f2bf1(float x) { return (unsigned short)(cvt_pk_bf16(x, 0.f) & 0xffffu); }
; __device__ __forceinline__ void gc_unit(LAS unsigned char* lds, int unit, const bf16_t* proj, const bf16_t* dSt, const float* gnorm, bf16_t* omix, int tid, int wave, int lane) {
;     const int n = unit & 63, bh = unit >> 6, b = bh >> 3, h = bh & 7;
;     const size_t row0 = (size_t)b * SEQ + n * 64;
;     bf16x8 sfr[8];
;     { const bf16_t* sp = dSt + ((size_t)unit * 256 + 32 * wave + (lane & 31)) * 128 + (lane >> 5) * 8;
; #pragma unroll
;       for (int ks = 0; ks < 8; ++ks) sfr[ks] = *(const bf16x8*)(sp + ks * 16); }
;     { const int t = tid >> 3, c0 = (tid & 7) * 16; const bf16_t* qp = proj + (row0 + t) * PROJ_LD + C_GQ + h * 128 + c0;
;       const u32x4 q0 = *(const u32x4*)qp, q1 = *(const u32x4*)(qp + 8), k0 = *(const u32x4*)(qp + (C_GK - C_GQ)), k1 = *(const u32x4*)(qp + (C_GK - C_GQ) + 8);
;       u32x4 vr[4]; load_v(vr, proj + row0 * PROJ_LD + C_GV + h * 256, tid);
;       *(LAS u32x4*)(lds + L_QD + t * 272 + c0 * 2) = q0; *(LAS u32x4*)(lds + L_QD + t * 272 + c0 * 2 + 16) = q1;
;       *(LAS u32x4*)(lds + L_KI + t * 272 + c0 * 2) = k0; *(LAS u32x4*)(lds + L_KI + t * 272 + c0 * 2 + 16) = k1;
;       store_v(lds, L_VT, vr, tid); }
;     __syncthreads();
;     const int r = lane & 31, hh = lane >> 5;
;     if (wave < 4) { const int ct = wave & 1, st = wave >> 1; f32x16 acc = {};
; #pragma unroll
;         for (int ks = 0; ks < 8; ++ks) { const bf16x8 a = *(const LAS bf16x8*)(lds + L_QD + (ct * 32 + r) * 272 + ks * 32 + hh * 16), bb = *(const LAS bf16x8*)(lds + L_KI + (st * 32 + r) * 272 + ks * 32 + hh * 16);
;             acc = __builtin_amdgcn_mfma_f32_32x32x16_bf16(a, bb, acc, 0, 0, 0); }
; #pragma unroll
;         for (int i = 0; i < 16; ++i) { const int c = ct * 32 + crow(i, hh), s2 = st * 32 + r; const float val = (s2 <= c) ? acc[i] : 0.f;
;             *(LAS unsigned short*)(lds + L_AT + c * 144 + s2 * 2) = f2bf1(val); } }
.LBB0_1006:
	s_cmp_lt_i32 s96, 6
	s_cselect_b64 s[4:5], -1, 0
	s_and_b64 s[0:1], s[4:5], s[0:1]
	s_cmpk_lt_i32 s94, 0x800
	s_cselect_b64 s[4:5], -1, 0
	s_and_b64 s[4:5], s[0:1], s[4:5]
	s_andn2_b64 vcc, exec, s[4:5]
	s_cbranch_vccnz .LBB0_1022
	v_lshrrev_b32_e32 v80, 3, v0
	v_and_b32_e32 v9, 48, v80
	v_lshrrev_b32_e32 v11, 2, v0
	v_readlane_b32 s3, v254, 5
	v_readlane_b32 s41, v254, 8
	v_and_or_b32 v9, v11, 8, v9
	s_lshl_b32 s3, s41, 5
	v_lshrrev_b32_e32 v9, 1, v9
	v_readlane_b32 s40, v254, 0
	v_and_b32_e32 v3, 31, v0
	v_lshlrev_b32_e32 v8, 12, v0
	v_and_or_b32 v9, v0, 3, v9
	s_cmpk_lt_u32 s40, 0x100
	v_or_b32_e32 v78, s3, v3
	v_lshrrev_b32_e32 v5, 5, v182
	v_and_b32_e32 v8, 0x4000, v8
	v_lshrrev_b32_e32 v11, 4, v0
	v_lshlrev_b32_e32 v9, 9, v9
	v_bfe_u32 v12, v0, 3, 2
	s_cselect_b64 s[42:43], -1, 0
	s_and_b32 s3, s3, 32
	s_movk_i32 s33, 0x110
	v_and_or_b32 v11, v11, 4, v12
	v_add3_u32 v12, 0, v8, v9
	v_or_b32_e32 v8, s3, v3
	s_lshl_b32 s4, s41, 4
	v_lshl_or_b32 v9, v5, 2, s3
	v_mad_u32_u24 v13, v8, s33, 0
	v_and_or_b32 v8, s4, 32, v3
	v_or_b32_e32 v19, 1, v9
	v_cmp_gt_u32_e64 s[6:7], v8, v19
	v_or_b32_e32 v19, 2, v9
	v_cmp_gt_u32_e64 s[8:9], v8, v19
	v_or_b32_e32 v19, 3, v9
	v_cmp_gt_u32_e64 s[10:11], v8, v19
	v_or_b32_e32 v19, 8, v9
	v_cmp_gt_u32_e64 s[12:13], v8, v19
	v_or_b32_e32 v19, 9, v9
	v_cmp_gt_u32_e64 s[14:15], v8, v19
	v_or_b32_e32 v19, 10, v9
	v_cmp_gt_u32_e64 s[16:17], v8, v19
	v_or_b32_e32 v19, 11, v9
	v_cmp_gt_u32_e64 s[18:19], v8, v19
	v_or_b32_e32 v19, 16, v9
	v_cmp_gt_u32_e64 s[20:21], v8, v19
	v_or_b32_e32 v19, 17, v9
	v_cmp_gt_u32_e64 s[22:23], v8, v19
	v_or_b32_e32 v19, 18, v9
	v_cmp_gt_u32_e64 s[24:25], v8, v19
	v_or_b32_e32 v19, 19, v9
	v_cmp_gt_u32_e64 s[26:27], v8, v19
	v_or_b32_e32 v19, 24, v9
	s_add_i32 s3, 0, 0x11800
	v_cmp_gt_u32_e64 s[28:29], v8, v19
	v_or_b32_e32 v19, 25, v9
	v_mov_b32_e32 v16, s3
	v_lshl_add_u32 v17, v8, 1, s3
	v_cmp_gt_u32_e64 s[4:5], v8, v9
	v_mul_u32_u24_e32 v18, 0x90, v9
	v_cmp_gt_u32_e64 s[30:31], v8, v19
	v_or_b32_e32 v19, 26, v9
	v_or_b32_e32 v9, 27, v9
	s_lshl_b32 s3, s41, 12
	v_mad_u32_u24 v15, v8, s33, 0
	v_cmp_gt_u32_e64 s[34:35], v8, v19
	v_cmp_gt_u32_e64 s[36:37], v8, v9
	s_and_b32 s3, s3, 0x7fffc000
	v_lshlrev_b32_e32 v8, 3, v0
	v_lshlrev_b32_e32 v9, 4, v182
	v_lshlrev_b32_e32 v20, 1, v0
	s_add_i32 s3, s3, 0
	v_and_b32_e32 v19, 0xc0, v9
	v_and_b32_e32 v20, 32, v20
	v_and_b32_e32 v8, 0x118, v8
	s_add_i32 s3, s3, 0x9800
	v_or3_b32 v8, v19, v20, v8
	v_mov_b32_e32 v79, 0
	s_movk_i32 s38, 0x90
	v_add_u32_e32 v81, s3, v8
	v_or_b32_e32 v8, 32, v182
	v_readlane_b32 s44, v254, 9
	v_mad_u32_u24 v7, v80, s33, 0
	v_mad_u32_u24 v19, v3, s38, v16
	v_mad_u32_u24 v16, v8, s38, v16
	v_mad_u32_u24 v3, v3, s33, 0
	v_mad_u32_u24 v20, v8, s33, 0
	s_movk_i32 s33, 0x1040
	v_add_u32_e32 v98, 0, v9
	v_lshlrev_b32_e32 v8, 3, v182
	v_mov_b32_e32 v9, v79
	v_readlane_b32 s45, v254, 10
	s_ashr_i32 s95, s94, 31
	v_lshlrev_b32_e32 v14, 4, v5
	s_bfe_u32 s3, s40, 0x20006
	v_mad_u32_u24 v5, v5, s33, 0
	s_lshl_b32 s33, s41, 3
	v_lshl_add_u64 v[82:83], s[44:45], 0, v[8:9]
	s_mul_i32 s52, s41, 0x2080
	v_lshlrev_b64 v[8:9], 8, v[78:79]
	s_lshl_b64 s[40:41], s[94:95], 16
	v_and_b32_e32 v22, 32, v0
	v_lshlrev_b32_e32 v2, 4, v0
	v_lshl_add_u64 v[8:9], s[40:41], 0, v[8:9]
	v_lshrrev_b32_e32 v22, 1, v22
	v_and_b32_e32 v2, 0x70, v2
	v_lshlrev_b32_e32 v4, 5, v0
	v_or_b32_e32 v8, v8, v22
	v_and_b32_e32 v4, 0xe0, v4
	v_mul_u32_u24_e32 v6, 0x1800, v80
	v_lshlrev_b32_e32 v10, 1, v2
	v_lshlrev_b32_e32 v11, 6, v11
	v_lshlrev_b32_e32 v21, 2, v78
	s_or_b32 s53, s33, 1
	v_lshl_add_u64 v[8:9], s[76:77], 0, v[8:9]
	s_mov_b64 s[40:41], 0xe0
	s_ashr_i32 s89, s88, 31
	v_lshlrev_b32_e32 v90, 1, v2
	v_mbcnt_lo_u32_b32 v2, -1, 0
	s_mov_b32 s39, 0
	s_mul_i32 s54, s53, 0x410
	s_or_b32 s55, s33, 2
	s_or_b32 s56, s33, 3
	s_or_b32 s57, s33, 4
	s_or_b32 s58, s33, 5
	s_or_b32 s59, s33, 6
	s_or_b32 s60, s33, 7
	s_lshl_b32 s61, s94, 6
	s_lshl_b32 s62, s88, 6
	v_lshl_add_u64 v[84:85], v[8:9], 0, s[40:41]
	s_lshl_b64 s[44:45], s[88:89], 16
	v_mov_b64_e32 v[86:87], s[92:93]
	s_movk_i32 s63, 0x3000
	v_mov_b64_e32 v[88:89], s[90:91]
	v_mov_b32_e32 v99, 0x3000
	v_mov_b32_e32 v91, v79
	v_lshlrev_b32_e32 v92, 1, v6
	v_mov_b32_e32 v93, v79
	v_lshlrev_b32_e32 v94, 1, v4
	v_mov_b32_e32 v95, v79
	s_mov_b64 s[46:47], 0x1000
	s_movk_i32 s64, 0x1000
	v_add_u32_e32 v100, v7, v10
	v_add_u32_e32 v101, v12, v11
	v_add_u32_e32 v102, v13, v14
	v_add_u32_e32 v103, v15, v14
	v_add_u32_e32 v104, v17, v18
	v_add_u32_e32 v105, v19, v14
	v_add_u32_e32 v106, v16, v14
	v_add_u32_e32 v107, v3, v14
	v_add_u32_e32 v108, v20, v14
	v_add_u32_e32 v109, v5, v21
	v_mov_b32_e32 v110, 0x358637bd
	s_mov_b32 s65, 0xf800000
	v_mov_b32_e32 v111, 0x260
	s_movk_i32 s66, 0x2000
	v_mbcnt_hi_u32_b32 v112, -1, v2
	flat_load_dwordx2 v[96:97], v[86:87] offset:48 sc0 sc1
	s_waitcnt vmcnt(0) lgkmcnt(0)
	s_branch .LBB0_1009
; #define LAS __attribute__((address_space(3)))
; __device__ __forceinline__ int v_rd_base(int lane) { return ((lane & 3) << 3) | (((lane >> 2) & 3) << 6) | (((lane >> 4) & 1) << 5) | (((lane >> 5) & 1) << 8); }
; __device__ __forceinline__ int crow(int r, int hi) { return (r & 3) + 8 * (r >> 2) + 4 * hi; }
; __device__ __forceinline__ void gc_unit(LAS unsigned char* lds, int unit, const bf16_t* proj, const bf16_t* dSt, const float* gnorm, bf16_t* omix, int tid, int wave, int lane) {
;     ...
;     f32x16 o0 = {}, o1 = {};
;     { const int vbase = (int)(uintptr_t)(lds + L_VT + (wave >> 2) * 16384) + mb::v_rd_base(lane); bf16x8 vf[4];
;       switch (wave & 3) {
;           case 0: GLA_FRAG(vf[0], vbase, 0, 0); GLA_FRAG(vf[1], vbase, 0, 1); GLA_FRAG(vf[2], vbase, 0, 2); GLA_FRAG(vf[3], vbase, 0, 3); break;
;           case 1: GLA_FRAG(vf[0], vbase, 1, 0); GLA_FRAG(vf[1], vbase, 1, 1); GLA_FRAG(vf[2], vbase, 1, 2); GLA_FRAG(vf[3], vbase, 1, 3); break;
;           case 2: GLA_FRAG(vf[0], vbase, 2, 0); GLA_FRAG(vf[1], vbase, 2, 1); GLA_FRAG(vf[2], vbase, 2, 2); GLA_FRAG(vf[3], vbase, 2, 3); break;
;           default: GLA_FRAG(vf[0], vbase, 3, 0); GLA_FRAG(vf[1], vbase, 3, 1); GLA_FRAG(vf[2], vbase, 3, 2); GLA_FRAG(vf[3], vbase, 3, 3); break;
;       }
; #pragma unroll
;       for (int ss = 0; ss < 4; ++ss) { const bf16x8 a0 = *(const LAS bf16x8*)(lds + L_AT + r * 144 + ss * 32 + hh * 16), a1 = *(const LAS bf16x8*)(lds + L_AT + (32 + r) * 144 + ss * 32 + hh * 16);
;           o0 = __builtin_amdgcn_mfma_f32_32x32x16_bf16(a0, vf[ss], o0, 0, 0, 0); o1 = __builtin_amdgcn_mfma_f32_32x32x16_bf16(a1, vf[ss], o1, 0, 0, 0); } }
;     {
; #pragma unroll
;       for (int ks = 0; ks < 8; ++ks) { const bf16x8 bb = sfr[ks];
;           const bf16x8 a0 = *(const LAS bf16x8*)(lds + L_QD + r * 272 + ks * 32 + hh * 16), a1 = *(const LAS bf16x8*)(lds + L_QD + (32 + r) * 272 + ks * 32 + hh * 16);
;           o0 = __builtin_amdgcn_mfma_f32_32x32x16_bf16(a0, bb, o0, 0, 0, 0); o1 = __builtin_amdgcn_mfma_f32_32x32x16_bf16(a1, bb, o1, 0, 0, 0); } }
;     __syncthreads();
; #pragma unroll
;     for (int i = 0; i < 16; ++i) { const int c = crow(i, hh); *(LAS float*)(lds + L_OT + c * 1040 + (32 * wave + r) * 4) = o0[i]; *(LAS float*)(lds + L_OT + (32 + c) * 1040 + (32 * wave + r) * 4) = o1[i]; }
;     __syncthreads();
.LBB0_1008:
	ds_read_b128 v[2:5], v105
	ds_read_b128 v[114:117], v105 offset:32
	ds_read_b128 v[22:25], v106
	ds_read_b128 v[118:121], v106 offset:32
	s_lshl_b32 s38, s38, 1
	s_add_u32 s50, s48, s33
	s_waitcnt lgkmcnt(3)
	v_mfma_f32_32x32x16_bf16 v[2:17], v[2:5], v[18:21], 0
	s_addc_u32 s51, s49, 0
	s_mul_i32 s40, s51, 0x3000
	s_mul_hi_u32 s41, s50, 0x3000
	s_add_i32 s41, s41, s40
	s_mul_i32 s40, s50, 0x3000
	s_add_u32 s40, s90, s40
	s_addc_u32 s41, s91, s41
	s_waitcnt lgkmcnt(1)
	v_mfma_f32_32x32x16_bf16 v[18:33], v[22:25], v[18:21], 0
	v_lshlrev_b32_e32 v78, 4, v182
	s_add_u32 s40, s40, s38
	s_addc_u32 s41, s41, 0
	s_mov_b64 s[98:99], 0x2000
	s_mov_b64 s[100:101], 0x3000
	v_lshlrev_b32_e32 v122, 3, v182
	v_mov_b32_e32 v123, 0
	v_lshl_add_u64 v[122:123], s[40:41], 0, v[122:123]
	v_lshl_add_u64 v[122:123], v[122:123], 0, s[98:99]
	global_load_dwordx2 v[126:127], v[122:123], off
	v_lshl_add_u64 v[122:123], v[122:123], 0, s[100:101]
	global_load_dwordx2 v[128:129], v[122:123], off
	v_lshl_add_u64 v[122:123], v[122:123], 0, s[100:101]
	global_load_dwordx2 v[130:131], v[122:123], off
	v_lshl_add_u64 v[122:123], v[122:123], 0, s[100:101]
	global_load_dwordx2 v[132:133], v[122:123], off
	v_lshl_add_u64 v[122:123], v[122:123], 0, s[100:101]
	global_load_dwordx2 v[134:135], v[122:123], off
	v_lshl_add_u64 v[122:123], v[122:123], 0, s[100:101]
	global_load_dwordx2 v[136:137], v[122:123], off
	v_lshl_add_u64 v[122:123], v[122:123], 0, s[100:101]
	global_load_dwordx2 v[138:139], v[122:123], off
	v_lshl_add_u64 v[122:123], v[122:123], 0, s[100:101]
	global_load_dwordx2 v[140:141], v[122:123], off
	v_lshl_add_u64 v[84:85], v[84:85], 0, s[44:45]
	v_mfma_f32_32x32x16_bf16 v[2:17], v[114:117], v[74:77], v[2:17]
	s_waitcnt lgkmcnt(0)
	v_mfma_f32_32x32x16_bf16 v[18:33], v[118:121], v[74:77], v[18:33]
	ds_read_b128 v[74:77], v105 offset:64
	ds_read_b128 v[114:117], v105 offset:96
	s_waitcnt lgkmcnt(1)
	v_mfma_f32_32x32x16_bf16 v[2:17], v[74:77], v[70:73], v[2:17]
	ds_read_b128 v[74:77], v106 offset:64
	ds_read_b128 v[118:121], v106 offset:96
	s_waitcnt lgkmcnt(1)
	v_mfma_f32_32x32x16_bf16 v[18:33], v[74:77], v[70:73], v[18:33]
	v_mfma_f32_32x32x16_bf16 v[2:17], v[114:117], v[66:69], v[2:17]
	s_waitcnt lgkmcnt(0)
	v_mfma_f32_32x32x16_bf16 v[18:33], v[118:121], v[66:69], v[18:33]
	ds_read_b128 v[66:69], v107 offset:4096
	ds_read_b128 v[70:73], v107 offset:4128
	s_waitcnt lgkmcnt(1)
	v_mfma_f32_32x32x16_bf16 v[2:17], v[66:69], v[38:41], v[2:17]
	ds_read_b128 v[66:69], v108 offset:4096
	ds_read_b128 v[74:77], v108 offset:4128
	s_waitcnt lgkmcnt(1)
	v_mfma_f32_32x32x16_bf16 v[18:33], v[66:69], v[38:41], v[18:33]
	v_mfma_f32_32x32x16_bf16 v[2:17], v[70:73], v[34:37], v[2:17]
	s_waitcnt lgkmcnt(0)
	v_mfma_f32_32x32x16_bf16 v[18:33], v[74:77], v[34:37], v[18:33]
	ds_read_b128 v[34:37], v107 offset:4160
	ds_read_b128 v[38:41], v107 offset:4192
	s_waitcnt lgkmcnt(1)
	v_mfma_f32_32x32x16_bf16 v[2:17], v[34:37], v[62:65], v[2:17]
	ds_read_b128 v[34:37], v108 offset:4160
	ds_read_b128 v[66:69], v108 offset:4192
	s_waitcnt lgkmcnt(1)
	v_mfma_f32_32x32x16_bf16 v[18:33], v[34:37], v[62:65], v[18:33]
	v_mfma_f32_32x32x16_bf16 v[2:17], v[38:41], v[58:61], v[2:17]
	ds_read_b128 v[34:37], v107 offset:4224
	ds_read_b128 v[38:41], v107 offset:4256
	s_waitcnt lgkmcnt(2)
	v_mfma_f32_32x32x16_bf16 v[18:33], v[66:69], v[58:61], v[18:33]
	s_waitcnt lgkmcnt(1)
	v_mfma_f32_32x32x16_bf16 v[2:17], v[34:37], v[54:57], v[2:17]
	ds_read_b128 v[34:37], v108 offset:4224
	ds_read_b128 v[58:61], v108 offset:4256
	s_waitcnt lgkmcnt(1)
	v_mfma_f32_32x32x16_bf16 v[18:33], v[34:37], v[54:57], v[18:33]
	v_mfma_f32_32x32x16_bf16 v[2:17], v[38:41], v[50:53], v[2:17]
	ds_read_b128 v[34:37], v107 offset:4288
	ds_read_b128 v[38:41], v107 offset:4320
	s_waitcnt lgkmcnt(2)
	v_mfma_f32_32x32x16_bf16 v[18:33], v[58:61], v[50:53], v[18:33]
	s_waitcnt lgkmcnt(1)
	v_mfma_f32_32x32x16_bf16 v[2:17], v[34:37], v[46:49], v[2:17]
	ds_read_b128 v[34:37], v108 offset:4288
	ds_read_b128 v[50:53], v108 offset:4320
	s_waitcnt lgkmcnt(0)
	s_barrier
	v_mfma_f32_32x32x16_bf16 v[18:33], v[34:37], v[46:49], v[18:33]
	v_mfma_f32_32x32x16_bf16 v[2:17], v[38:41], v[42:45], v[2:17]
	v_mfma_f32_32x32x16_bf16 v[18:33], v[50:53], v[42:45], v[18:33]
	s_nop 10
	ds_write_b32 v109, v2 offset:4096
	v_add_u32_e32 v2, s52, v98
	ds_write_b32 v109, v18 offset:37376
	ds_write_b32 v109, v3 offset:5136
	ds_write_b32 v109, v19 offset:38416
	ds_write_b32 v109, v4 offset:6176
	ds_write_b32 v109, v20 offset:39456
	ds_write_b32 v109, v5 offset:7216
	ds_write_b32 v109, v21 offset:40496
	ds_write_b32 v109, v6 offset:12416
	ds_write_b32 v109, v22 offset:45696
	ds_write_b32 v109, v7 offset:13456
	ds_write_b32 v109, v23 offset:46736
	ds_write_b32 v109, v8 offset:14496
	ds_write_b32 v109, v24 offset:47776
	ds_write_b32 v109, v9 offset:15536
	ds_write_b32 v109, v25 offset:48816
	ds_write_b32 v109, v10 offset:20736
	ds_write_b32 v109, v26 offset:54016
	ds_write_b32 v109, v11 offset:21776
	ds_write_b32 v109, v27 offset:55056
	ds_write_b32 v109, v12 offset:22816
	ds_write_b32 v109, v28 offset:56096
	ds_write_b32 v109, v13 offset:23856
	ds_write_b32 v109, v29 offset:57136
	ds_write_b32 v109, v14 offset:29056
	ds_write_b32 v109, v30 offset:62336
	ds_write_b32 v109, v15 offset:30096
	ds_write_b32 v109, v31 offset:63376
	ds_write_b32 v109, v16 offset:31136
	ds_write_b32 v109, v32 offset:64416
	ds_write_b32 v109, v17 offset:32176
	ds_write_b32 v109, v33 offset:65456
	s_waitcnt lgkmcnt(0)
	s_barrier
; #define LAS __attribute__((address_space(3)))
; __device__ __forceinline__ unsigned cvt_pk_bf16(float lo, float hi) { unsigned r; asm volatile("v_cvt_pk_bf16_f32 %0, %1, %2" : "=v"(r) : "v"(lo), "v"(hi)); return r; }
; __device__ __forceinline__ float bflo(unsigned w) { return __uint_as_float(w << 16); }
; __device__ __forceinline__ float bfhi(unsigned w) { return __uint_as_float(w & 0xffff0000u); }
; __device__ __forceinline__ void gc_unit(LAS unsigned char* lds, int unit, const bf16_t* proj, const bf16_t* dSt, const float* gnorm, bf16_t* omix, int tid, int wave, int lane) {
;     ...
;     const f32x4 g = *((const f32x4*)gnorm + lane);
; #pragma unroll
;     for (int rr = 0; rr < 8; ++rr) { const int c = 8 * wave + rr; const f32x4 v = *(const LAS f32x4*)(lds + L_OT + c * 1040 + lane * 16);
;         float ss = (v[0] * v[0] + v[1] * v[1]) + (v[2] * v[2] + v[3] * v[3]);
; #pragma unroll
;         for (int o = 1; o < 64; o <<= 1) ss += __shfl_xor(ss, o);
;         const float rs = 1.0f / sqrtf(ss * (1.0f / 256.0f) + EPS);
;         const u32x2 gw2 = *((const u32x2*)(proj + (row0 + c) * PROJ_LD + C_GOUT + h * 256) + lane);
;         const float z0 = bflo(gw2.x), z1 = bfhi(gw2.x), z2 = bflo(gw2.y), z3 = bfhi(gw2.y);
;         const float p0 = v[0] * rs * g[0] * (z0 / (1.0f + __expf(-z0))), p1 = v[1] * rs * g[1] * (z1 / (1.0f + __expf(-z1)));
;         const float p2 = v[2] * rs * g[2] * (z2 / (1.0f + __expf(-z2))), p3 = v[3] * rs * g[3] * (z3 / (1.0f + __expf(-z3)));
;         u32x2 w; w.x = cvt_pk_bf16(p0, p1); w.y = cvt_pk_bf16(p2, p3); *((u32x2*)(omix + (row0 + c) * DM + h * 256) + lane) = w; }
	ds_read_b128 v[14:17], v2 offset:4096
	v_and_b32_e32 v2, 64, v112
	v_add_u32_e32 v6, 64, v2
	s_waitcnt lgkmcnt(0)
	v_mul_f32_e32 v2, v15, v15
	v_mul_f32_e32 v3, v17, v17
	v_fmac_f32_e32 v2, v14, v14
	v_fmac_f32_e32 v3, v16, v16
	v_add_f32_e32 v4, v2, v3
	v_xor_b32_e32 v2, 1, v112
	v_cmp_lt_i32_e32 vcc, v2, v6
	s_nop 1
	v_cndmask_b32_e32 v2, v112, v2, vcc
	v_lshlrev_b32_e32 v8, 2, v2
	ds_bpermute_b32 v5, v8, v4
	v_lshl_add_u64 v[2:3], v[96:97], 0, v[78:79]
	v_lshlrev_b32_e32 v78, 3, v182
	s_waitcnt lgkmcnt(0)
	v_add_f32_e32 v7, v4, v5
	v_xor_b32_e32 v4, 2, v112
	v_cmp_lt_i32_e32 vcc, v4, v6
	s_nop 1
	v_cndmask_b32_e32 v4, v112, v4, vcc
	v_lshlrev_b32_e32 v9, 2, v4
	v_lshl_add_u64 v[4:5], s[40:41], 0, v[78:79]
	v_add_co_u32_e32 v4, vcc, s66, v4
	ds_bpermute_b32 v10, v9, v7
	s_nop 0
	v_addc_co_u32_e32 v5, vcc, 0, v5, vcc
	v_xor_b32_e32 v4, 4, v112
	v_cmp_lt_i32_e32 vcc, v4, v6
	s_waitcnt lgkmcnt(0)
	v_add_f32_e32 v7, v7, v10
	v_cndmask_b32_e32 v4, v112, v4, vcc
	v_lshlrev_b32_e32 v10, 2, v4
	ds_bpermute_b32 v11, v10, v7
	flat_load_dwordx4 v[2:5], v[2:3]
	s_waitcnt lgkmcnt(0)
	v_add_f32_e32 v7, v7, v11
	v_xor_b32_e32 v11, 8, v112
	v_cmp_lt_i32_e32 vcc, v11, v6
	s_nop 1
	v_cndmask_b32_e32 v11, v112, v11, vcc
	v_lshlrev_b32_e32 v11, 2, v11
	ds_bpermute_b32 v12, v11, v7
	s_waitcnt lgkmcnt(0)
	v_add_f32_e32 v7, v7, v12
	v_xor_b32_e32 v12, 16, v112
	v_cmp_lt_i32_e32 vcc, v12, v6
	s_nop 1
	v_cndmask_b32_e32 v12, v112, v12, vcc
	v_lshlrev_b32_e32 v12, 2, v12
	ds_bpermute_b32 v13, v12, v7
	s_waitcnt lgkmcnt(0)
	v_add_f32_e32 v7, v7, v13
	v_xor_b32_e32 v13, 32, v112
	v_cmp_lt_i32_e32 vcc, v13, v6
	s_nop 1
	v_cndmask_b32_e32 v6, v112, v13, vcc
	v_lshlrev_b32_e32 v13, 2, v6
	ds_bpermute_b32 v6, v13, v7
	s_waitcnt lgkmcnt(0)
	v_add_f32_e32 v6, v7, v6
	v_fmamk_f32 v6, v6, 0x3b800000, v110
	v_mul_f32_e32 v7, 0x4f800000, v6
	v_cmp_gt_f32_e32 vcc, s65, v6
	s_nop 1
	v_cndmask_b32_e32 v6, v6, v7, vcc
	v_sqrt_f32_e32 v7, v6
	s_nop 0
	v_add_u32_e32 v20, -1, v7
	v_fma_f32 v21, -v20, v7, v6
	v_cmp_ge_f32_e64 s[40:41], 0, v21
	v_add_u32_e32 v21, 1, v7
	s_nop 0
	v_cndmask_b32_e64 v20, v7, v20, s[40:41]
	v_fma_f32 v7, -v21, v7, v6
	v_cmp_lt_f32_e64 s[40:41], 0, v7
	s_nop 1
	v_cndmask_b32_e64 v7, v20, v21, s[40:41]
	v_mul_f32_e32 v20, 0x37800000, v7
	v_cndmask_b32_e32 v7, v7, v20, vcc
	v_cmp_class_f32_e32 vcc, v6, v111
	s_nop 1
	v_cndmask_b32_e32 v20, v7, v6, vcc
	v_div_scale_f32 v21, s[40:41], v20, v20, 1.0
	v_rcp_f32_e32 v22, v21
	v_lshl_add_u64 v[6:7], v[82:83], 0, s[38:39]
	v_fma_f32 v23, -v21, v22, 1.0
	v_fmac_f32_e32 v22, v23, v22
	v_div_scale_f32 v23, vcc, 1.0, v20, 1.0
	v_mul_f32_e32 v24, v23, v22
	v_fma_f32 v25, -v21, v24, v23
	v_fmac_f32_e32 v24, v25, v22
	v_fma_f32 v21, -v21, v24, v23
	v_div_fmas_f32 v21, v21, v22, v24
	s_waitcnt vmcnt(0)
	v_mov_b32_e32 v18, v126
	v_mov_b32_e32 v19, v127
	v_lshlrev_b32_e32 v22, 16, v18
	v_mul_f32_e32 v23, 0xbfb8aa3b, v22
	v_exp_f32_e32 v23, v23
	v_div_fixup_f32 v20, v21, v20, 1.0
	v_and_b32_e32 v18, 0xffff0000, v18
	v_mul_f32_e32 v14, v14, v20
	v_add_f32_e32 v21, 1.0, v23
	v_div_scale_f32 v23, s[40:41], v21, v21, v22
	v_rcp_f32_e32 v24, v23
	v_mul_f32_e32 v14, v2, v14
	v_lshlrev_b32_e32 v25, 16, v19
	v_mul_f32_e32 v15, v15, v20
	v_fma_f32 v26, -v23, v24, 1.0
	v_fmac_f32_e32 v24, v26, v24
	v_div_scale_f32 v26, vcc, v22, v21, v22
	v_mul_f32_e32 v27, v26, v24
	v_fma_f32 v28, -v23, v27, v26
	v_fmac_f32_e32 v27, v28, v24
	v_fma_f32 v23, -v23, v27, v26
	v_mul_f32_e32 v26, 0xbfb8aa3b, v18
	v_exp_f32_e32 v26, v26
	v_div_fmas_f32 v23, v23, v24, v27
	v_div_fixup_f32 v21, v23, v21, v22
	v_mul_f32_e32 v14, v21, v14
	v_add_f32_e32 v22, 1.0, v26
	v_div_scale_f32 v23, s[40:41], v22, v22, v18
	v_rcp_f32_e32 v24, v23
	v_mul_f32_e32 v15, v3, v15
	v_and_b32_e32 v19, 0xffff0000, v19
	v_mul_f32_e32 v16, v16, v20
	v_fma_f32 v21, -v23, v24, 1.0
	v_fmac_f32_e32 v24, v21, v24
	v_div_scale_f32 v21, vcc, v18, v22, v18
	v_mul_f32_e32 v26, v21, v24
	v_fma_f32 v27, -v23, v26, v21
	v_fmac_f32_e32 v26, v27, v24
	v_fma_f32 v21, -v23, v26, v21
	v_mul_f32_e32 v23, 0xbfb8aa3b, v25
	v_exp_f32_e32 v23, v23
	v_div_fmas_f32 v21, v21, v24, v26
	v_div_fixup_f32 v18, v21, v22, v18
	v_mul_f32_e32 v15, v18, v15
	v_add_f32_e32 v21, 1.0, v23
	v_div_scale_f32 v22, s[40:41], v21, v21, v25
	v_rcp_f32_e32 v23, v22
	v_mul_f32_e32 v16, v4, v16
	v_mul_f32_e32 v17, v17, v20
	v_mul_f32_e32 v17, v5, v17
	v_fma_f32 v18, -v22, v23, 1.0
	v_fmac_f32_e32 v23, v18, v23
	v_div_scale_f32 v18, vcc, v25, v21, v25
	v_mul_f32_e32 v24, v18, v23
	v_fma_f32 v26, -v22, v24, v18
	v_fmac_f32_e32 v24, v26, v23
	v_fma_f32 v18, -v22, v24, v18
	v_mul_f32_e32 v22, 0xbfb8aa3b, v19
	v_exp_f32_e32 v22, v22
	v_div_fmas_f32 v18, v18, v23, v24
	v_div_fixup_f32 v18, v18, v21, v25
	v_mul_f32_e32 v16, v18, v16
	v_add_f32_e32 v21, 1.0, v22
	v_div_scale_f32 v22, s[40:41], v21, v21, v19
	v_rcp_f32_e32 v23, v22
	s_lshl_b64 s[40:41], s[50:51], 13
	s_add_u32 s50, s48, s53
	s_addc_u32 s51, s49, 0
	v_fma_f32 v18, -v22, v23, 1.0
	v_fmac_f32_e32 v23, v18, v23
	v_div_scale_f32 v18, vcc, v19, v21, v19
	v_mul_f32_e32 v20, v18, v23
	v_fma_f32 v24, -v22, v20, v18
	v_fmac_f32_e32 v20, v24, v23
	v_fma_f32 v18, -v22, v20, v18
	v_div_fmas_f32 v18, v18, v23, v20
	v_div_fixup_f32 v18, v18, v21, v19
	v_mul_f32_e32 v17, v18, v17
	v_cvt_pk_bf16_f32 v14, v14, v15
	v_cvt_pk_bf16_f32 v15, v16, v17
	v_lshl_add_u64 v[16:17], v[6:7], 0, s[40:41]
	s_mul_i32 s40, s51, 0x3000
	s_mul_hi_u32 s41, s50, 0x3000
	s_add_i32 s41, s41, s40
	s_mul_i32 s40, s50, 0x3000
	s_add_u32 s40, s90, s40
	s_addc_u32 s41, s91, s41
	s_add_u32 s40, s40, s38
	s_addc_u32 s41, s41, 0
	v_lshl_add_u64 v[20:21], s[40:41], 0, v[78:79]
	v_add_co_u32_e32 v20, vcc, s66, v20
	global_store_dwordx2 v[16:17], v[14:15], off
	s_nop 0
	v_addc_co_u32_e32 v21, vcc, 0, v21, vcc
	v_add_u32_e32 v14, s54, v98
	ds_read_b128 v[16:19], v14 offset:4096
	s_waitcnt lgkmcnt(0)
; #define LAS __attribute__((address_space(3)))
; __device__ __forceinline__ unsigned cvt_pk_bf16(float lo, float hi) { unsigned r; asm volatile("v_cvt_pk_bf16_f32 %0, %1, %2" : "=v"(r) : "v"(lo), "v"(hi)); return r; }
; __device__ __forceinline__ float bflo(unsigned w) { return __uint_as_float(w << 16); }
; __device__ __forceinline__ float bfhi(unsigned w) { return __uint_as_float(w & 0xffff0000u); }
; __device__ __forceinline__ void gc_unit(LAS unsigned char* lds, int unit, const bf16_t* proj, const bf16_t* dSt, const float* gnorm, bf16_t* omix, int tid, int wave, int lane) {
;     ...
;     for (int rr = 0; rr < 8; ++rr) { const int c = 8 * wave + rr; const f32x4 v = *(const LAS f32x4*)(lds + L_OT + c * 1040 + lane * 16);
;         float ss = (v[0] * v[0] + v[1] * v[1]) + (v[2] * v[2] + v[3] * v[3]);
; #pragma unroll
;         for (int o = 1; o < 64; o <<= 1) ss += __shfl_xor(ss, o);
;         const float rs = 1.0f / sqrtf(ss * (1.0f / 256.0f) + EPS);
;         const u32x2 gw2 = *((const u32x2*)(proj + (row0 + c) * PROJ_LD + C_GOUT + h * 256) + lane);
;         const float z0 = bflo(gw2.x), z1 = bfhi(gw2.x), z2 = bflo(gw2.y), z3 = bfhi(gw2.y);
;         const float p0 = v[0] * rs * g[0] * (z0 / (1.0f + __expf(-z0))), p1 = v[1] * rs * g[1] * (z1 / (1.0f + __expf(-z1)));
;         const float p2 = v[2] * rs * g[2] * (z2 / (1.0f + __expf(-z2))), p3 = v[3] * rs * g[3] * (z3 / (1.0f + __expf(-z3)));
;         u32x2 w; w.x = cvt_pk_bf16(p0, p1); w.y = cvt_pk_bf16(p2, p3); *((u32x2*)(omix + (row0 + c) * DM + h * 256) + lane) = w; }
	v_mul_f32_e32 v15, v17, v17
	v_mul_f32_e32 v22, v19, v19
	v_fmac_f32_e32 v15, v16, v16
	v_fmac_f32_e32 v22, v18, v18
	v_add_f32_e32 v15, v15, v22
	ds_bpermute_b32 v22, v8, v15
	s_waitcnt lgkmcnt(0)
	v_add_f32_e32 v15, v15, v22
	ds_bpermute_b32 v22, v9, v15
	s_waitcnt lgkmcnt(0)
	v_add_f32_e32 v15, v15, v22
	ds_bpermute_b32 v22, v10, v15
	s_waitcnt lgkmcnt(0)
	v_add_f32_e32 v15, v15, v22
	ds_bpermute_b32 v22, v11, v15
	s_waitcnt lgkmcnt(0)
	v_add_f32_e32 v15, v15, v22
	ds_bpermute_b32 v22, v12, v15
	s_waitcnt lgkmcnt(0)
	v_add_f32_e32 v15, v15, v22
	ds_bpermute_b32 v22, v13, v15
	s_waitcnt lgkmcnt(0)
	v_add_f32_e32 v15, v15, v22
	v_fmamk_f32 v15, v15, 0x3b800000, v110
	v_mul_f32_e32 v22, 0x4f800000, v15
	v_cmp_gt_f32_e32 vcc, s65, v15
	s_nop 1
	v_cndmask_b32_e32 v15, v15, v22, vcc
	v_sqrt_f32_e32 v22, v15
	s_nop 0
	v_add_u32_e32 v23, -1, v22
	v_fma_f32 v24, -v23, v22, v15
	v_cmp_ge_f32_e64 s[40:41], 0, v24
	v_add_u32_e32 v24, 1, v22
	s_nop 0
	v_cndmask_b32_e64 v23, v22, v23, s[40:41]
	v_fma_f32 v22, -v24, v22, v15
	v_cmp_lt_f32_e64 s[40:41], 0, v22
	s_nop 1
	v_cndmask_b32_e64 v22, v23, v24, s[40:41]
	v_mul_f32_e32 v23, 0x37800000, v22
	v_cndmask_b32_e32 v22, v22, v23, vcc
	v_cmp_class_f32_e32 vcc, v15, v111
	s_nop 1
	v_cndmask_b32_e32 v15, v22, v15, vcc
	v_div_scale_f32 v22, s[40:41], v15, v15, 1.0
	v_rcp_f32_e32 v23, v22
	s_nop 0
	v_fma_f32 v24, -v22, v23, 1.0
	v_fmac_f32_e32 v23, v24, v23
	v_div_scale_f32 v24, vcc, 1.0, v15, 1.0
	v_mul_f32_e32 v25, v24, v23
	v_fma_f32 v26, -v22, v25, v24
	v_fmac_f32_e32 v25, v26, v23
	v_fma_f32 v22, -v22, v25, v24
	v_div_fmas_f32 v22, v22, v23, v25
	v_mov_b32_e32 v20, v128
	v_mov_b32_e32 v21, v129
	v_lshlrev_b32_e32 v23, 16, v20
	v_mul_f32_e32 v24, 0xbfb8aa3b, v23
	v_exp_f32_e32 v24, v24
	v_and_b32_e32 v20, 0xffff0000, v20
	v_div_fixup_f32 v15, v22, v15, 1.0
	v_mul_f32_e32 v16, v16, v15
	v_add_f32_e32 v24, 1.0, v24
	v_div_scale_f32 v25, s[40:41], v24, v24, v23
	v_rcp_f32_e32 v26, v25
	v_mul_f32_e32 v16, v2, v16
	v_lshlrev_b32_e32 v22, 16, v21
	v_mul_f32_e32 v17, v17, v15
	v_fma_f32 v27, -v25, v26, 1.0
	v_fmac_f32_e32 v26, v27, v26
	v_div_scale_f32 v27, vcc, v23, v24, v23
	v_mul_f32_e32 v28, v27, v26
	v_fma_f32 v29, -v25, v28, v27
	v_fmac_f32_e32 v28, v29, v26
	v_fma_f32 v25, -v25, v28, v27
	v_mul_f32_e32 v27, 0xbfb8aa3b, v20
	v_exp_f32_e32 v27, v27
	v_div_fmas_f32 v25, v25, v26, v28
	v_div_fixup_f32 v23, v25, v24, v23
	v_mul_f32_e32 v16, v23, v16
	v_add_f32_e32 v24, 1.0, v27
	v_div_scale_f32 v25, s[40:41], v24, v24, v20
	v_rcp_f32_e32 v26, v25
	v_mul_f32_e32 v17, v3, v17
	v_and_b32_e32 v21, 0xffff0000, v21
	v_mul_f32_e32 v18, v18, v15
	v_fma_f32 v23, -v25, v26, 1.0
	v_fmac_f32_e32 v26, v23, v26
	v_div_scale_f32 v23, vcc, v20, v24, v20
	v_mul_f32_e32 v27, v23, v26
	v_fma_f32 v28, -v25, v27, v23
	v_fmac_f32_e32 v27, v28, v26
	v_fma_f32 v23, -v25, v27, v23
	v_mul_f32_e32 v25, 0xbfb8aa3b, v22
	v_exp_f32_e32 v25, v25
	v_div_fmas_f32 v23, v23, v26, v27
	v_div_fixup_f32 v20, v23, v24, v20
	v_mul_f32_e32 v17, v20, v17
	v_add_f32_e32 v23, 1.0, v25
	v_div_scale_f32 v24, s[40:41], v23, v23, v22
	v_rcp_f32_e32 v25, v24
	v_mul_f32_e32 v15, v19, v15
	v_mul_f32_e32 v18, v4, v18
	v_mul_f32_e32 v15, v5, v15
	v_fma_f32 v20, -v24, v25, 1.0
	v_fmac_f32_e32 v25, v20, v25
	v_div_scale_f32 v20, vcc, v22, v23, v22
	v_mul_f32_e32 v26, v20, v25
	v_fma_f32 v27, -v24, v26, v20
	v_fmac_f32_e32 v26, v27, v25
	v_fma_f32 v20, -v24, v26, v20
	v_mul_f32_e32 v24, 0xbfb8aa3b, v21
	v_exp_f32_e32 v24, v24
	v_div_fmas_f32 v20, v20, v25, v26
	v_div_fixup_f32 v20, v20, v23, v22
	v_mul_f32_e32 v18, v20, v18
	v_add_f32_e32 v22, 1.0, v24
	v_div_scale_f32 v23, s[40:41], v22, v22, v21
	v_rcp_f32_e32 v24, v23
	s_lshl_b64 s[40:41], s[50:51], 13
	s_add_u32 s50, s48, s55
	s_addc_u32 s51, s49, 0
	v_fma_f32 v19, -v23, v24, 1.0
	v_fmac_f32_e32 v24, v19, v24
	v_div_scale_f32 v19, vcc, v21, v22, v21
	v_mul_f32_e32 v20, v19, v24
	v_fma_f32 v25, -v23, v20, v19
	v_fmac_f32_e32 v20, v25, v24
	v_fma_f32 v19, -v23, v20, v19
	v_div_fmas_f32 v19, v19, v24, v20
	v_div_fixup_f32 v19, v19, v22, v21
	v_mul_f32_e32 v15, v19, v15
	v_cvt_pk_bf16_f32 v16, v16, v17
	v_cvt_pk_bf16_f32 v17, v18, v15
	v_lshl_add_u64 v[18:19], v[6:7], 0, s[40:41]
	s_mul_i32 s40, s51, 0x3000
	s_mul_hi_u32 s41, s50, 0x3000
	s_add_i32 s41, s41, s40
	s_mul_i32 s40, s50, 0x3000
	s_add_u32 s40, s90, s40
	s_addc_u32 s41, s91, s41
	s_add_u32 s40, s40, s38
	s_addc_u32 s41, s41, 0
	v_lshl_add_u64 v[20:21], s[40:41], 0, v[78:79]
	v_add_co_u32_e32 v20, vcc, s66, v20
	global_store_dwordx2 v[18:19], v[16:17], off
	s_nop 0
	v_addc_co_u32_e32 v21, vcc, 0, v21, vcc
	ds_read_b128 v[16:19], v14 offset:5136
	s_waitcnt lgkmcnt(0)
	v_mul_f32_e32 v15, v17, v17
	v_mul_f32_e32 v22, v19, v19
	v_fmac_f32_e32 v15, v16, v16
	v_fmac_f32_e32 v22, v18, v18
	v_add_f32_e32 v15, v15, v22
	ds_bpermute_b32 v22, v8, v15
	s_waitcnt lgkmcnt(0)
	v_add_f32_e32 v15, v15, v22
	ds_bpermute_b32 v22, v9, v15
	s_waitcnt lgkmcnt(0)
	v_add_f32_e32 v15, v15, v22
	ds_bpermute_b32 v22, v10, v15
	s_waitcnt lgkmcnt(0)
	v_add_f32_e32 v15, v15, v22
	ds_bpermute_b32 v22, v11, v15
	s_waitcnt lgkmcnt(0)
	v_add_f32_e32 v15, v15, v22
	ds_bpermute_b32 v22, v12, v15
	s_waitcnt lgkmcnt(0)
	v_add_f32_e32 v15, v15, v22
	ds_bpermute_b32 v22, v13, v15
	s_waitcnt lgkmcnt(0)
; #define LAS __attribute__((address_space(3)))
; __device__ __forceinline__ unsigned cvt_pk_bf16(float lo, float hi) { unsigned r; asm volatile("v_cvt_pk_bf16_f32 %0, %1, %2" : "=v"(r) : "v"(lo), "v"(hi)); return r; }
; __device__ __forceinline__ float bflo(unsigned w) { return __uint_as_float(w << 16); }
; __device__ __forceinline__ float bfhi(unsigned w) { return __uint_as_float(w & 0xffff0000u); }
; __device__ __forceinline__ void gc_unit(LAS unsigned char* lds, int unit, const bf16_t* proj, const bf16_t* dSt, const float* gnorm, bf16_t* omix, int tid, int wave, int lane) {
;     ...
;     for (int rr = 0; rr < 8; ++rr) { const int c = 8 * wave + rr; const f32x4 v = *(const LAS f32x4*)(lds + L_OT + c * 1040 + lane * 16);
;         float ss = (v[0] * v[0] + v[1] * v[1]) + (v[2] * v[2] + v[3] * v[3]);
; #pragma unroll
;         for (int o = 1; o < 64; o <<= 1) ss += __shfl_xor(ss, o);
;         const float rs = 1.0f / sqrtf(ss * (1.0f / 256.0f) + EPS);
;         const u32x2 gw2 = *((const u32x2*)(proj + (row0 + c) * PROJ_LD + C_GOUT + h * 256) + lane);
;         const float z0 = bflo(gw2.x), z1 = bfhi(gw2.x), z2 = bflo(gw2.y), z3 = bfhi(gw2.y);
;         const float p0 = v[0] * rs * g[0] * (z0 / (1.0f + __expf(-z0))), p1 = v[1] * rs * g[1] * (z1 / (1.0f + __expf(-z1)));
;         const float p2 = v[2] * rs * g[2] * (z2 / (1.0f + __expf(-z2))), p3 = v[3] * rs * g[3] * (z3 / (1.0f + __expf(-z3)));
;         u32x2 w; w.x = cvt_pk_bf16(p0, p1); w.y = cvt_pk_bf16(p2, p3); *((u32x2*)(omix + (row0 + c) * DM + h * 256) + lane) = w; }
	v_add_f32_e32 v15, v15, v22
	v_fmamk_f32 v15, v15, 0x3b800000, v110
	v_mul_f32_e32 v22, 0x4f800000, v15
	v_cmp_gt_f32_e32 vcc, s65, v15
	s_nop 1
	v_cndmask_b32_e32 v15, v15, v22, vcc
	v_sqrt_f32_e32 v22, v15
	s_nop 0
	v_add_u32_e32 v23, -1, v22
	v_fma_f32 v24, -v23, v22, v15
	v_cmp_ge_f32_e64 s[40:41], 0, v24
	v_add_u32_e32 v24, 1, v22
	s_nop 0
	v_cndmask_b32_e64 v23, v22, v23, s[40:41]
	v_fma_f32 v22, -v24, v22, v15
	v_cmp_lt_f32_e64 s[40:41], 0, v22
	s_nop 1
	v_cndmask_b32_e64 v22, v23, v24, s[40:41]
	v_mul_f32_e32 v23, 0x37800000, v22
	v_cndmask_b32_e32 v22, v22, v23, vcc
	v_cmp_class_f32_e32 vcc, v15, v111
	s_nop 1
	v_cndmask_b32_e32 v15, v22, v15, vcc
	v_div_scale_f32 v22, s[40:41], v15, v15, 1.0
	v_rcp_f32_e32 v23, v22
	s_nop 0
	v_fma_f32 v24, -v22, v23, 1.0
	v_fmac_f32_e32 v23, v24, v23
	v_div_scale_f32 v24, vcc, 1.0, v15, 1.0
	v_mul_f32_e32 v25, v24, v23
	v_fma_f32 v26, -v22, v25, v24
	v_fmac_f32_e32 v25, v26, v23
	v_fma_f32 v22, -v22, v25, v24
	v_div_fmas_f32 v22, v22, v23, v25
	v_mov_b32_e32 v20, v130
	v_mov_b32_e32 v21, v131
	v_lshlrev_b32_e32 v23, 16, v20
	v_mul_f32_e32 v24, 0xbfb8aa3b, v23
	v_exp_f32_e32 v24, v24
	v_and_b32_e32 v20, 0xffff0000, v20
	v_div_fixup_f32 v15, v22, v15, 1.0
	v_mul_f32_e32 v16, v16, v15
	v_add_f32_e32 v24, 1.0, v24
	v_div_scale_f32 v25, s[40:41], v24, v24, v23
	v_rcp_f32_e32 v26, v25
	v_mul_f32_e32 v16, v2, v16
	v_lshlrev_b32_e32 v22, 16, v21
	v_mul_f32_e32 v17, v17, v15
	v_fma_f32 v27, -v25, v26, 1.0
	v_fmac_f32_e32 v26, v27, v26
	v_div_scale_f32 v27, vcc, v23, v24, v23
	v_mul_f32_e32 v28, v27, v26
	v_fma_f32 v29, -v25, v28, v27
	v_fmac_f32_e32 v28, v29, v26
	v_fma_f32 v25, -v25, v28, v27
	v_mul_f32_e32 v27, 0xbfb8aa3b, v20
	v_exp_f32_e32 v27, v27
	v_div_fmas_f32 v25, v25, v26, v28
	v_div_fixup_f32 v23, v25, v24, v23
	v_mul_f32_e32 v16, v23, v16
	v_add_f32_e32 v24, 1.0, v27
	v_div_scale_f32 v25, s[40:41], v24, v24, v20
	v_rcp_f32_e32 v26, v25
	v_mul_f32_e32 v17, v3, v17
	v_and_b32_e32 v21, 0xffff0000, v21
	v_mul_f32_e32 v18, v18, v15
	v_fma_f32 v23, -v25, v26, 1.0
	v_fmac_f32_e32 v26, v23, v26
	v_div_scale_f32 v23, vcc, v20, v24, v20
	v_mul_f32_e32 v27, v23, v26
	v_fma_f32 v28, -v25, v27, v23
	v_fmac_f32_e32 v27, v28, v26
	v_fma_f32 v23, -v25, v27, v23
	v_mul_f32_e32 v25, 0xbfb8aa3b, v22
	v_exp_f32_e32 v25, v25
	v_div_fmas_f32 v23, v23, v26, v27
	v_div_fixup_f32 v20, v23, v24, v20
	v_mul_f32_e32 v17, v20, v17
	v_add_f32_e32 v23, 1.0, v25
	v_div_scale_f32 v24, s[40:41], v23, v23, v22
	v_rcp_f32_e32 v25, v24
	v_mul_f32_e32 v15, v19, v15
	v_mul_f32_e32 v18, v4, v18
	v_mul_f32_e32 v15, v5, v15
	v_fma_f32 v20, -v24, v25, 1.0
	v_fmac_f32_e32 v25, v20, v25
	v_div_scale_f32 v20, vcc, v22, v23, v22
	v_mul_f32_e32 v26, v20, v25
	v_fma_f32 v27, -v24, v26, v20
	v_fmac_f32_e32 v26, v27, v25
	v_fma_f32 v20, -v24, v26, v20
	v_mul_f32_e32 v24, 0xbfb8aa3b, v21
	v_exp_f32_e32 v24, v24
	v_div_fmas_f32 v20, v20, v25, v26
	v_div_fixup_f32 v20, v20, v23, v22
	v_mul_f32_e32 v18, v20, v18
	v_add_f32_e32 v22, 1.0, v24
	v_div_scale_f32 v23, s[40:41], v22, v22, v21
	v_rcp_f32_e32 v24, v23
	s_lshl_b64 s[40:41], s[50:51], 13
	s_add_u32 s50, s48, s56
	s_addc_u32 s51, s49, 0
	v_fma_f32 v19, -v23, v24, 1.0
	v_fmac_f32_e32 v24, v19, v24
	v_div_scale_f32 v19, vcc, v21, v22, v21
	v_mul_f32_e32 v20, v19, v24
	v_fma_f32 v25, -v23, v20, v19
	v_fmac_f32_e32 v20, v25, v24
	v_fma_f32 v19, -v23, v20, v19
	v_div_fmas_f32 v19, v19, v24, v20
	v_div_fixup_f32 v19, v19, v22, v21
	v_mul_f32_e32 v15, v19, v15
	v_cvt_pk_bf16_f32 v16, v16, v17
	v_cvt_pk_bf16_f32 v17, v18, v15
	v_lshl_add_u64 v[18:19], v[6:7], 0, s[40:41]
	s_mul_i32 s40, s51, 0x3000
	s_mul_hi_u32 s41, s50, 0x3000
	s_add_i32 s41, s41, s40
	s_mul_i32 s40, s50, 0x3000
	s_add_u32 s40, s90, s40
	s_addc_u32 s41, s91, s41
	s_add_u32 s40, s40, s38
	s_addc_u32 s41, s41, 0
	v_lshl_add_u64 v[20:21], s[40:41], 0, v[78:79]
	v_add_co_u32_e32 v20, vcc, s66, v20
	global_store_dwordx2 v[18:19], v[16:17], off
	s_nop 0
	v_addc_co_u32_e32 v21, vcc, 0, v21, vcc
	ds_read_b128 v[16:19], v14 offset:6176
	s_waitcnt lgkmcnt(0)
	v_mul_f32_e32 v15, v17, v17
	v_mul_f32_e32 v22, v19, v19
	v_fmac_f32_e32 v15, v16, v16
	v_fmac_f32_e32 v22, v18, v18
	v_add_f32_e32 v15, v15, v22
	ds_bpermute_b32 v22, v8, v15
	s_waitcnt lgkmcnt(0)
	v_add_f32_e32 v15, v15, v22
	ds_bpermute_b32 v22, v9, v15
	s_waitcnt lgkmcnt(0)
	v_add_f32_e32 v15, v15, v22
	ds_bpermute_b32 v22, v10, v15
	s_waitcnt lgkmcnt(0)
	v_add_f32_e32 v15, v15, v22
	ds_bpermute_b32 v22, v11, v15
	s_waitcnt lgkmcnt(0)
	v_add_f32_e32 v15, v15, v22
	ds_bpermute_b32 v22, v12, v15
	s_waitcnt lgkmcnt(0)
	v_add_f32_e32 v15, v15, v22
	ds_bpermute_b32 v22, v13, v15
	s_waitcnt lgkmcnt(0)
; #define LAS __attribute__((address_space(3)))
; __device__ __forceinline__ unsigned cvt_pk_bf16(float lo, float hi) { unsigned r; asm volatile("v_cvt_pk_bf16_f32 %0, %1, %2" : "=v"(r) : "v"(lo), "v"(hi)); return r; }
; __device__ __forceinline__ float bflo(unsigned w) { return __uint_as_float(w << 16); }
; __device__ __forceinline__ float bfhi(unsigned w) { return __uint_as_float(w & 0xffff0000u); }
; __device__ __forceinline__ void gc_unit(LAS unsigned char* lds, int unit, const bf16_t* proj, const bf16_t* dSt, const float* gnorm, bf16_t* omix, int tid, int wave, int lane) {
;     ...
;     for (int rr = 0; rr < 8; ++rr) { const int c = 8 * wave + rr; const f32x4 v = *(const LAS f32x4*)(lds + L_OT + c * 1040 + lane * 16);
;         float ss = (v[0] * v[0] + v[1] * v[1]) + (v[2] * v[2] + v[3] * v[3]);
; #pragma unroll
;         for (int o = 1; o < 64; o <<= 1) ss += __shfl_xor(ss, o);
;         const float rs = 1.0f / sqrtf(ss * (1.0f / 256.0f) + EPS);
;         const u32x2 gw2 = *((const u32x2*)(proj + (row0 + c) * PROJ_LD + C_GOUT + h * 256) + lane);
;         const float z0 = bflo(gw2.x), z1 = bfhi(gw2.x), z2 = bflo(gw2.y), z3 = bfhi(gw2.y);
;         const float p0 = v[0] * rs * g[0] * (z0 / (1.0f + __expf(-z0))), p1 = v[1] * rs * g[1] * (z1 / (1.0f + __expf(-z1)));
;         const float p2 = v[2] * rs * g[2] * (z2 / (1.0f + __expf(-z2))), p3 = v[3] * rs * g[3] * (z3 / (1.0f + __expf(-z3)));
;         u32x2 w; w.x = cvt_pk_bf16(p0, p1); w.y = cvt_pk_bf16(p2, p3); *((u32x2*)(omix + (row0 + c) * DM + h * 256) + lane) = w; }
	v_add_f32_e32 v15, v15, v22
	v_fmamk_f32 v15, v15, 0x3b800000, v110
	v_mul_f32_e32 v22, 0x4f800000, v15
	v_cmp_gt_f32_e32 vcc, s65, v15
	s_nop 1
	v_cndmask_b32_e32 v15, v15, v22, vcc
	v_sqrt_f32_e32 v22, v15
	s_nop 0
	v_add_u32_e32 v23, -1, v22
	v_fma_f32 v24, -v23, v22, v15
	v_cmp_ge_f32_e64 s[40:41], 0, v24
	v_add_u32_e32 v24, 1, v22
	s_nop 0
	v_cndmask_b32_e64 v23, v22, v23, s[40:41]
	v_fma_f32 v22, -v24, v22, v15
	v_cmp_lt_f32_e64 s[40:41], 0, v22
	s_nop 1
	v_cndmask_b32_e64 v22, v23, v24, s[40:41]
	v_mul_f32_e32 v23, 0x37800000, v22
	v_cndmask_b32_e32 v22, v22, v23, vcc
	v_cmp_class_f32_e32 vcc, v15, v111
	s_nop 1
	v_cndmask_b32_e32 v15, v22, v15, vcc
	v_div_scale_f32 v22, s[40:41], v15, v15, 1.0
	v_rcp_f32_e32 v23, v22
	s_nop 0
	v_fma_f32 v24, -v22, v23, 1.0
	v_fmac_f32_e32 v23, v24, v23
	v_div_scale_f32 v24, vcc, 1.0, v15, 1.0
	v_mul_f32_e32 v25, v24, v23
	v_fma_f32 v26, -v22, v25, v24
	v_fmac_f32_e32 v25, v26, v23
	v_fma_f32 v22, -v22, v25, v24
	v_div_fmas_f32 v22, v22, v23, v25
	v_mov_b32_e32 v20, v132
	v_mov_b32_e32 v21, v133
	v_lshlrev_b32_e32 v23, 16, v20
	v_mul_f32_e32 v24, 0xbfb8aa3b, v23
	v_exp_f32_e32 v24, v24
	v_and_b32_e32 v20, 0xffff0000, v20
	v_div_fixup_f32 v15, v22, v15, 1.0
	v_mul_f32_e32 v16, v16, v15
	v_add_f32_e32 v24, 1.0, v24
	v_div_scale_f32 v25, s[40:41], v24, v24, v23
	v_rcp_f32_e32 v26, v25
	v_mul_f32_e32 v16, v2, v16
	v_lshlrev_b32_e32 v22, 16, v21
	v_mul_f32_e32 v17, v17, v15
	v_fma_f32 v27, -v25, v26, 1.0
	v_fmac_f32_e32 v26, v27, v26
	v_div_scale_f32 v27, vcc, v23, v24, v23
	v_mul_f32_e32 v28, v27, v26
	v_fma_f32 v29, -v25, v28, v27
	v_fmac_f32_e32 v28, v29, v26
	v_fma_f32 v25, -v25, v28, v27
	v_mul_f32_e32 v27, 0xbfb8aa3b, v20
	v_exp_f32_e32 v27, v27
	v_div_fmas_f32 v25, v25, v26, v28
	v_div_fixup_f32 v23, v25, v24, v23
	v_mul_f32_e32 v16, v23, v16
	v_add_f32_e32 v24, 1.0, v27
	v_div_scale_f32 v25, s[40:41], v24, v24, v20
	v_rcp_f32_e32 v26, v25
	v_mul_f32_e32 v17, v3, v17
	v_and_b32_e32 v21, 0xffff0000, v21
	v_mul_f32_e32 v18, v18, v15
	v_fma_f32 v23, -v25, v26, 1.0
	v_fmac_f32_e32 v26, v23, v26
	v_div_scale_f32 v23, vcc, v20, v24, v20
	v_mul_f32_e32 v27, v23, v26
	v_fma_f32 v28, -v25, v27, v23
	v_fmac_f32_e32 v27, v28, v26
	v_fma_f32 v23, -v25, v27, v23
	v_mul_f32_e32 v25, 0xbfb8aa3b, v22
	v_exp_f32_e32 v25, v25
	v_div_fmas_f32 v23, v23, v26, v27
	v_div_fixup_f32 v20, v23, v24, v20
	v_mul_f32_e32 v17, v20, v17
	v_add_f32_e32 v23, 1.0, v25
	v_div_scale_f32 v24, s[40:41], v23, v23, v22
	v_rcp_f32_e32 v25, v24
	v_mul_f32_e32 v15, v19, v15
	v_mul_f32_e32 v18, v4, v18
	v_mul_f32_e32 v15, v5, v15
	v_fma_f32 v20, -v24, v25, 1.0
	v_fmac_f32_e32 v25, v20, v25
	v_div_scale_f32 v20, vcc, v22, v23, v22
	v_mul_f32_e32 v26, v20, v25
	v_fma_f32 v27, -v24, v26, v20
	v_fmac_f32_e32 v26, v27, v25
	v_fma_f32 v20, -v24, v26, v20
	v_mul_f32_e32 v24, 0xbfb8aa3b, v21
	v_exp_f32_e32 v24, v24
	v_div_fmas_f32 v20, v20, v25, v26
	v_div_fixup_f32 v20, v20, v23, v22
	v_mul_f32_e32 v18, v20, v18
	v_add_f32_e32 v22, 1.0, v24
	v_div_scale_f32 v23, s[40:41], v22, v22, v21
	v_rcp_f32_e32 v24, v23
	s_lshl_b64 s[40:41], s[50:51], 13
	s_add_u32 s50, s48, s57
	s_addc_u32 s51, s49, 0
	v_fma_f32 v19, -v23, v24, 1.0
	v_fmac_f32_e32 v24, v19, v24
	v_div_scale_f32 v19, vcc, v21, v22, v21
	v_mul_f32_e32 v20, v19, v24
	v_fma_f32 v25, -v23, v20, v19
	v_fmac_f32_e32 v20, v25, v24
	v_fma_f32 v19, -v23, v20, v19
	v_div_fmas_f32 v19, v19, v24, v20
	v_div_fixup_f32 v19, v19, v22, v21
	v_mul_f32_e32 v15, v19, v15
	v_cvt_pk_bf16_f32 v16, v16, v17
	v_cvt_pk_bf16_f32 v17, v18, v15
	v_lshl_add_u64 v[18:19], v[6:7], 0, s[40:41]
	s_mul_i32 s40, s51, 0x3000
	s_mul_hi_u32 s41, s50, 0x3000
	s_add_i32 s41, s41, s40
	s_mul_i32 s40, s50, 0x3000
	s_add_u32 s40, s90, s40
	s_addc_u32 s41, s91, s41
	s_add_u32 s40, s40, s38
	s_addc_u32 s41, s41, 0
	v_lshl_add_u64 v[20:21], s[40:41], 0, v[78:79]
	v_add_co_u32_e32 v20, vcc, s66, v20
	global_store_dwordx2 v[18:19], v[16:17], off
	s_nop 0
	v_addc_co_u32_e32 v21, vcc, 0, v21, vcc
	ds_read_b128 v[16:19], v14 offset:7216
	s_waitcnt lgkmcnt(0)
	v_mul_f32_e32 v15, v17, v17
	v_mul_f32_e32 v22, v19, v19
	v_fmac_f32_e32 v15, v16, v16
	v_fmac_f32_e32 v22, v18, v18
	v_add_f32_e32 v15, v15, v22
	ds_bpermute_b32 v22, v8, v15
	s_waitcnt lgkmcnt(0)
	v_add_f32_e32 v15, v15, v22
	ds_bpermute_b32 v22, v9, v15
	s_waitcnt lgkmcnt(0)
	v_add_f32_e32 v15, v15, v22
	ds_bpermute_b32 v22, v10, v15
	s_waitcnt lgkmcnt(0)
	v_add_f32_e32 v15, v15, v22
	ds_bpermute_b32 v22, v11, v15
	s_waitcnt lgkmcnt(0)
	v_add_f32_e32 v15, v15, v22
	ds_bpermute_b32 v22, v12, v15
	s_waitcnt lgkmcnt(0)
	v_add_f32_e32 v15, v15, v22
	ds_bpermute_b32 v22, v13, v15
	s_waitcnt lgkmcnt(0)
; #define LAS __attribute__((address_space(3)))
; __device__ __forceinline__ unsigned cvt_pk_bf16(float lo, float hi) { unsigned r; asm volatile("v_cvt_pk_bf16_f32 %0, %1, %2" : "=v"(r) : "v"(lo), "v"(hi)); return r; }
; __device__ __forceinline__ float bflo(unsigned w) { return __uint_as_float(w << 16); }
; __device__ __forceinline__ float bfhi(unsigned w) { return __uint_as_float(w & 0xffff0000u); }
; __device__ __forceinline__ void gc_unit(LAS unsigned char* lds, int unit, const bf16_t* proj, const bf16_t* dSt, const float* gnorm, bf16_t* omix, int tid, int wave, int lane) {
;     ...
;     for (int rr = 0; rr < 8; ++rr) { const int c = 8 * wave + rr; const f32x4 v = *(const LAS f32x4*)(lds + L_OT + c * 1040 + lane * 16);
;         float ss = (v[0] * v[0] + v[1] * v[1]) + (v[2] * v[2] + v[3] * v[3]);
; #pragma unroll
;         for (int o = 1; o < 64; o <<= 1) ss += __shfl_xor(ss, o);
;         const float rs = 1.0f / sqrtf(ss * (1.0f / 256.0f) + EPS);
;         const u32x2 gw2 = *((const u32x2*)(proj + (row0 + c) * PROJ_LD + C_GOUT + h * 256) + lane);
;         const float z0 = bflo(gw2.x), z1 = bfhi(gw2.x), z2 = bflo(gw2.y), z3 = bfhi(gw2.y);
;         const float p0 = v[0] * rs * g[0] * (z0 / (1.0f + __expf(-z0))), p1 = v[1] * rs * g[1] * (z1 / (1.0f + __expf(-z1)));
;         const float p2 = v[2] * rs * g[2] * (z2 / (1.0f + __expf(-z2))), p3 = v[3] * rs * g[3] * (z3 / (1.0f + __expf(-z3)));
;         u32x2 w; w.x = cvt_pk_bf16(p0, p1); w.y = cvt_pk_bf16(p2, p3); *((u32x2*)(omix + (row0 + c) * DM + h * 256) + lane) = w; }
	v_add_f32_e32 v15, v15, v22
	v_fmamk_f32 v15, v15, 0x3b800000, v110
	v_mul_f32_e32 v22, 0x4f800000, v15
	v_cmp_gt_f32_e32 vcc, s65, v15
	s_nop 1
	v_cndmask_b32_e32 v15, v15, v22, vcc
	v_sqrt_f32_e32 v22, v15
	s_nop 0
	v_add_u32_e32 v23, -1, v22
	v_fma_f32 v24, -v23, v22, v15
	v_cmp_ge_f32_e64 s[40:41], 0, v24
	v_add_u32_e32 v24, 1, v22
	s_nop 0
	v_cndmask_b32_e64 v23, v22, v23, s[40:41]
	v_fma_f32 v22, -v24, v22, v15
	v_cmp_lt_f32_e64 s[40:41], 0, v22
	s_nop 1
	v_cndmask_b32_e64 v22, v23, v24, s[40:41]
	v_mul_f32_e32 v23, 0x37800000, v22
	v_cndmask_b32_e32 v22, v22, v23, vcc
	v_cmp_class_f32_e32 vcc, v15, v111
	s_nop 1
	v_cndmask_b32_e32 v15, v22, v15, vcc
	v_div_scale_f32 v22, s[40:41], v15, v15, 1.0
	v_rcp_f32_e32 v23, v22
	s_nop 0
	v_fma_f32 v24, -v22, v23, 1.0
	v_fmac_f32_e32 v23, v24, v23
	v_div_scale_f32 v24, vcc, 1.0, v15, 1.0
	v_mul_f32_e32 v25, v24, v23
	v_fma_f32 v26, -v22, v25, v24
	v_fmac_f32_e32 v25, v26, v23
	v_fma_f32 v22, -v22, v25, v24
	v_div_fmas_f32 v22, v22, v23, v25
	v_mov_b32_e32 v20, v134
	v_mov_b32_e32 v21, v135
	v_lshlrev_b32_e32 v23, 16, v20
	v_mul_f32_e32 v24, 0xbfb8aa3b, v23
	v_exp_f32_e32 v24, v24
	v_and_b32_e32 v20, 0xffff0000, v20
	v_div_fixup_f32 v15, v22, v15, 1.0
	v_mul_f32_e32 v16, v16, v15
	v_add_f32_e32 v24, 1.0, v24
	v_div_scale_f32 v25, s[40:41], v24, v24, v23
	v_rcp_f32_e32 v26, v25
	v_mul_f32_e32 v16, v2, v16
	v_lshlrev_b32_e32 v22, 16, v21
	v_mul_f32_e32 v17, v17, v15
	v_fma_f32 v27, -v25, v26, 1.0
	v_fmac_f32_e32 v26, v27, v26
	v_div_scale_f32 v27, vcc, v23, v24, v23
	v_mul_f32_e32 v28, v27, v26
	v_fma_f32 v29, -v25, v28, v27
	v_fmac_f32_e32 v28, v29, v26
	v_fma_f32 v25, -v25, v28, v27
	v_mul_f32_e32 v27, 0xbfb8aa3b, v20
	v_exp_f32_e32 v27, v27
	v_div_fmas_f32 v25, v25, v26, v28
	v_div_fixup_f32 v23, v25, v24, v23
	v_mul_f32_e32 v16, v23, v16
	v_add_f32_e32 v24, 1.0, v27
	v_div_scale_f32 v25, s[40:41], v24, v24, v20
	v_rcp_f32_e32 v26, v25
	v_mul_f32_e32 v17, v3, v17
	v_and_b32_e32 v21, 0xffff0000, v21
	v_mul_f32_e32 v18, v18, v15
	v_fma_f32 v23, -v25, v26, 1.0
	v_fmac_f32_e32 v26, v23, v26
	v_div_scale_f32 v23, vcc, v20, v24, v20
	v_mul_f32_e32 v27, v23, v26
	v_fma_f32 v28, -v25, v27, v23
	v_fmac_f32_e32 v27, v28, v26
	v_fma_f32 v23, -v25, v27, v23
	v_mul_f32_e32 v25, 0xbfb8aa3b, v22
	v_exp_f32_e32 v25, v25
	v_div_fmas_f32 v23, v23, v26, v27
	v_div_fixup_f32 v20, v23, v24, v20
	v_mul_f32_e32 v17, v20, v17
	v_add_f32_e32 v23, 1.0, v25
	v_div_scale_f32 v24, s[40:41], v23, v23, v22
	v_rcp_f32_e32 v25, v24
	v_mul_f32_e32 v15, v19, v15
	v_mul_f32_e32 v18, v4, v18
	v_mul_f32_e32 v15, v5, v15
	v_fma_f32 v20, -v24, v25, 1.0
	v_fmac_f32_e32 v25, v20, v25
	v_div_scale_f32 v20, vcc, v22, v23, v22
	v_mul_f32_e32 v26, v20, v25
	v_fma_f32 v27, -v24, v26, v20
	v_fmac_f32_e32 v26, v27, v25
	v_fma_f32 v20, -v24, v26, v20
	v_mul_f32_e32 v24, 0xbfb8aa3b, v21
	v_exp_f32_e32 v24, v24
	v_div_fmas_f32 v20, v20, v25, v26
	v_div_fixup_f32 v20, v20, v23, v22
	v_mul_f32_e32 v18, v20, v18
	v_add_f32_e32 v22, 1.0, v24
	v_div_scale_f32 v23, s[40:41], v22, v22, v21
	v_rcp_f32_e32 v24, v23
	s_lshl_b64 s[40:41], s[50:51], 13
	s_add_u32 s50, s48, s58
	s_addc_u32 s51, s49, 0
	v_fma_f32 v19, -v23, v24, 1.0
	v_fmac_f32_e32 v24, v19, v24
	v_div_scale_f32 v19, vcc, v21, v22, v21
	v_mul_f32_e32 v20, v19, v24
	v_fma_f32 v25, -v23, v20, v19
	v_fmac_f32_e32 v20, v25, v24
	v_fma_f32 v19, -v23, v20, v19
	v_div_fmas_f32 v19, v19, v24, v20
	v_div_fixup_f32 v19, v19, v22, v21
	v_mul_f32_e32 v15, v19, v15
	v_cvt_pk_bf16_f32 v16, v16, v17
	v_cvt_pk_bf16_f32 v17, v18, v15
	v_lshl_add_u64 v[18:19], v[6:7], 0, s[40:41]
	s_mul_i32 s40, s51, 0x3000
	s_mul_hi_u32 s41, s50, 0x3000
	s_add_i32 s41, s41, s40
	s_mul_i32 s40, s50, 0x3000
	s_add_u32 s40, s90, s40
	s_addc_u32 s41, s91, s41
	s_add_u32 s40, s40, s38
	s_addc_u32 s41, s41, 0
	v_lshl_add_u64 v[20:21], s[40:41], 0, v[78:79]
	v_add_co_u32_e32 v20, vcc, s66, v20
	global_store_dwordx2 v[18:19], v[16:17], off
	s_nop 0
	v_addc_co_u32_e32 v21, vcc, 0, v21, vcc
	ds_read_b128 v[16:19], v14 offset:8256
	s_waitcnt lgkmcnt(0)
	v_mul_f32_e32 v15, v17, v17
	v_mul_f32_e32 v22, v19, v19
	v_fmac_f32_e32 v15, v16, v16
	v_fmac_f32_e32 v22, v18, v18
	v_add_f32_e32 v15, v15, v22
	ds_bpermute_b32 v22, v8, v15
	s_waitcnt lgkmcnt(0)
	v_add_f32_e32 v15, v15, v22
	ds_bpermute_b32 v22, v9, v15
	s_waitcnt lgkmcnt(0)
	v_add_f32_e32 v15, v15, v22
	ds_bpermute_b32 v22, v10, v15
	s_waitcnt lgkmcnt(0)
	v_add_f32_e32 v15, v15, v22
	ds_bpermute_b32 v22, v11, v15
	s_waitcnt lgkmcnt(0)
	v_add_f32_e32 v15, v15, v22
	ds_bpermute_b32 v22, v12, v15
	s_waitcnt lgkmcnt(0)
	v_add_f32_e32 v15, v15, v22
	ds_bpermute_b32 v22, v13, v15
	s_waitcnt lgkmcnt(0)
; #define LAS __attribute__((address_space(3)))
; __device__ __forceinline__ unsigned cvt_pk_bf16(float lo, float hi) { unsigned r; asm volatile("v_cvt_pk_bf16_f32 %0, %1, %2" : "=v"(r) : "v"(lo), "v"(hi)); return r; }
; __device__ __forceinline__ float bflo(unsigned w) { return __uint_as_float(w << 16); }
; __device__ __forceinline__ float bfhi(unsigned w) { return __uint_as_float(w & 0xffff0000u); }
; __device__ __forceinline__ void gc_unit(LAS unsigned char* lds, int unit, const bf16_t* proj, const bf16_t* dSt, const float* gnorm, bf16_t* omix, int tid, int wave, int lane) {
;     ...
;     for (int rr = 0; rr < 8; ++rr) { const int c = 8 * wave + rr; const f32x4 v = *(const LAS f32x4*)(lds + L_OT + c * 1040 + lane * 16);
;         float ss = (v[0] * v[0] + v[1] * v[1]) + (v[2] * v[2] + v[3] * v[3]);
; #pragma unroll
;         for (int o = 1; o < 64; o <<= 1) ss += __shfl_xor(ss, o);
;         const float rs = 1.0f / sqrtf(ss * (1.0f / 256.0f) + EPS);
;         const u32x2 gw2 = *((const u32x2*)(proj + (row0 + c) * PROJ_LD + C_GOUT + h * 256) + lane);
;         const float z0 = bflo(gw2.x), z1 = bfhi(gw2.x), z2 = bflo(gw2.y), z3 = bfhi(gw2.y);
;         const float p0 = v[0] * rs * g[0] * (z0 / (1.0f + __expf(-z0))), p1 = v[1] * rs * g[1] * (z1 / (1.0f + __expf(-z1)));
;         const float p2 = v[2] * rs * g[2] * (z2 / (1.0f + __expf(-z2))), p3 = v[3] * rs * g[3] * (z3 / (1.0f + __expf(-z3)));
;         u32x2 w; w.x = cvt_pk_bf16(p0, p1); w.y = cvt_pk_bf16(p2, p3); *((u32x2*)(omix + (row0 + c) * DM + h * 256) + lane) = w; }
	v_add_f32_e32 v15, v15, v22
	v_fmamk_f32 v15, v15, 0x3b800000, v110
	v_mul_f32_e32 v22, 0x4f800000, v15
	v_cmp_gt_f32_e32 vcc, s65, v15
	s_nop 1
	v_cndmask_b32_e32 v15, v15, v22, vcc
	v_sqrt_f32_e32 v22, v15
	s_nop 0
	v_add_u32_e32 v23, -1, v22
	v_fma_f32 v24, -v23, v22, v15
	v_cmp_ge_f32_e64 s[40:41], 0, v24
	v_add_u32_e32 v24, 1, v22
	s_nop 0
	v_cndmask_b32_e64 v23, v22, v23, s[40:41]
	v_fma_f32 v22, -v24, v22, v15
	v_cmp_lt_f32_e64 s[40:41], 0, v22
	s_nop 1
	v_cndmask_b32_e64 v22, v23, v24, s[40:41]
	v_mul_f32_e32 v23, 0x37800000, v22
	v_cndmask_b32_e32 v22, v22, v23, vcc
	v_cmp_class_f32_e32 vcc, v15, v111
	s_nop 1
	v_cndmask_b32_e32 v15, v22, v15, vcc
	v_div_scale_f32 v22, s[40:41], v15, v15, 1.0
	v_rcp_f32_e32 v23, v22
	s_nop 0
	v_fma_f32 v24, -v22, v23, 1.0
	v_fmac_f32_e32 v23, v24, v23
	v_div_scale_f32 v24, vcc, 1.0, v15, 1.0
	v_mul_f32_e32 v25, v24, v23
	v_fma_f32 v26, -v22, v25, v24
	v_fmac_f32_e32 v25, v26, v23
	v_fma_f32 v22, -v22, v25, v24
	v_div_fmas_f32 v22, v22, v23, v25
	v_mov_b32_e32 v20, v136
	v_mov_b32_e32 v21, v137
	v_lshlrev_b32_e32 v23, 16, v20
	v_mul_f32_e32 v24, 0xbfb8aa3b, v23
	v_exp_f32_e32 v24, v24
	v_and_b32_e32 v20, 0xffff0000, v20
	v_div_fixup_f32 v15, v22, v15, 1.0
	v_mul_f32_e32 v16, v16, v15
	v_add_f32_e32 v24, 1.0, v24
	v_div_scale_f32 v25, s[40:41], v24, v24, v23
	v_rcp_f32_e32 v26, v25
	v_mul_f32_e32 v16, v2, v16
	v_lshlrev_b32_e32 v22, 16, v21
	v_mul_f32_e32 v17, v17, v15
	v_fma_f32 v27, -v25, v26, 1.0
	v_fmac_f32_e32 v26, v27, v26
	v_div_scale_f32 v27, vcc, v23, v24, v23
	v_mul_f32_e32 v28, v27, v26
	v_fma_f32 v29, -v25, v28, v27
	v_fmac_f32_e32 v28, v29, v26
	v_fma_f32 v25, -v25, v28, v27
	v_mul_f32_e32 v27, 0xbfb8aa3b, v20
	v_exp_f32_e32 v27, v27
	v_div_fmas_f32 v25, v25, v26, v28
	v_div_fixup_f32 v23, v25, v24, v23
	v_mul_f32_e32 v16, v23, v16
	v_add_f32_e32 v24, 1.0, v27
	v_div_scale_f32 v25, s[40:41], v24, v24, v20
	v_rcp_f32_e32 v26, v25
	v_mul_f32_e32 v17, v3, v17
	v_and_b32_e32 v21, 0xffff0000, v21
	v_mul_f32_e32 v18, v18, v15
	v_fma_f32 v23, -v25, v26, 1.0
	v_fmac_f32_e32 v26, v23, v26
	v_div_scale_f32 v23, vcc, v20, v24, v20
	v_mul_f32_e32 v27, v23, v26
	v_fma_f32 v28, -v25, v27, v23
	v_fmac_f32_e32 v27, v28, v26
	v_fma_f32 v23, -v25, v27, v23
	v_mul_f32_e32 v25, 0xbfb8aa3b, v22
	v_exp_f32_e32 v25, v25
	v_div_fmas_f32 v23, v23, v26, v27
	v_div_fixup_f32 v20, v23, v24, v20
	v_mul_f32_e32 v17, v20, v17
	v_add_f32_e32 v23, 1.0, v25
	v_div_scale_f32 v24, s[40:41], v23, v23, v22
	v_rcp_f32_e32 v25, v24
	v_mul_f32_e32 v15, v19, v15
	v_mul_f32_e32 v18, v4, v18
	v_mul_f32_e32 v15, v5, v15
	v_fma_f32 v20, -v24, v25, 1.0
	v_fmac_f32_e32 v25, v20, v25
	v_div_scale_f32 v20, vcc, v22, v23, v22
	v_mul_f32_e32 v26, v20, v25
	v_fma_f32 v27, -v24, v26, v20
	v_fmac_f32_e32 v26, v27, v25
	v_fma_f32 v20, -v24, v26, v20
	v_mul_f32_e32 v24, 0xbfb8aa3b, v21
	v_exp_f32_e32 v24, v24
	v_div_fmas_f32 v20, v20, v25, v26
	v_div_fixup_f32 v20, v20, v23, v22
	v_mul_f32_e32 v18, v20, v18
	v_add_f32_e32 v22, 1.0, v24
	v_div_scale_f32 v23, s[40:41], v22, v22, v21
	v_rcp_f32_e32 v24, v23
	s_lshl_b64 s[40:41], s[50:51], 13
	s_add_u32 s50, s48, s59
	s_addc_u32 s51, s49, 0
	v_fma_f32 v19, -v23, v24, 1.0
	v_fmac_f32_e32 v24, v19, v24
	v_div_scale_f32 v19, vcc, v21, v22, v21
	v_mul_f32_e32 v20, v19, v24
	v_fma_f32 v25, -v23, v20, v19
	v_fmac_f32_e32 v20, v25, v24
	v_fma_f32 v19, -v23, v20, v19
	v_div_fmas_f32 v19, v19, v24, v20
	v_div_fixup_f32 v19, v19, v22, v21
	v_mul_f32_e32 v15, v19, v15
	v_cvt_pk_bf16_f32 v16, v16, v17
	v_cvt_pk_bf16_f32 v17, v18, v15
	v_lshl_add_u64 v[18:19], v[6:7], 0, s[40:41]
	s_mul_i32 s40, s51, 0x3000
	s_mul_hi_u32 s41, s50, 0x3000
	s_add_i32 s41, s41, s40
	s_mul_i32 s40, s50, 0x3000
	s_add_u32 s40, s90, s40
	s_addc_u32 s41, s91, s41
	s_add_u32 s40, s40, s38
	s_addc_u32 s41, s41, 0
	v_lshl_add_u64 v[20:21], s[40:41], 0, v[78:79]
	v_add_co_u32_e32 v20, vcc, s66, v20
	global_store_dwordx2 v[18:19], v[16:17], off
	s_nop 0
	v_addc_co_u32_e32 v21, vcc, 0, v21, vcc
	ds_read_b128 v[16:19], v14 offset:9296
	s_waitcnt lgkmcnt(0)
	v_mul_f32_e32 v15, v17, v17
	v_mul_f32_e32 v22, v19, v19
	v_fmac_f32_e32 v15, v16, v16
	v_fmac_f32_e32 v22, v18, v18
	v_add_f32_e32 v15, v15, v22
	ds_bpermute_b32 v22, v8, v15
	s_waitcnt lgkmcnt(0)
	v_add_f32_e32 v15, v15, v22
	ds_bpermute_b32 v22, v9, v15
	s_waitcnt lgkmcnt(0)
	v_add_f32_e32 v15, v15, v22
	ds_bpermute_b32 v22, v10, v15
	s_waitcnt lgkmcnt(0)
	v_add_f32_e32 v15, v15, v22
	ds_bpermute_b32 v22, v11, v15
	s_waitcnt lgkmcnt(0)
	v_add_f32_e32 v15, v15, v22
	ds_bpermute_b32 v22, v12, v15
	s_waitcnt lgkmcnt(0)
	v_add_f32_e32 v15, v15, v22
	ds_bpermute_b32 v22, v13, v15
	s_waitcnt lgkmcnt(0)
; #define LAS __attribute__((address_space(3)))
; __device__ __forceinline__ unsigned cvt_pk_bf16(float lo, float hi) { unsigned r; asm volatile("v_cvt_pk_bf16_f32 %0, %1, %2" : "=v"(r) : "v"(lo), "v"(hi)); return r; }
; __device__ __forceinline__ float bflo(unsigned w) { return __uint_as_float(w << 16); }
; __device__ __forceinline__ float bfhi(unsigned w) { return __uint_as_float(w & 0xffff0000u); }
; #define gla_norm_g ARGP(6)
; __device__ __forceinline__ void gc_unit(LAS unsigned char* lds, int unit, const bf16_t* proj, const bf16_t* dSt, const float* gnorm, bf16_t* omix, int tid, int wave, int lane) {
;     ...
;     for (int rr = 0; rr < 8; ++rr) { const int c = 8 * wave + rr; const f32x4 v = *(const LAS f32x4*)(lds + L_OT + c * 1040 + lane * 16);
;         float ss = (v[0] * v[0] + v[1] * v[1]) + (v[2] * v[2] + v[3] * v[3]);
; #pragma unroll
;         for (int o = 1; o < 64; o <<= 1) ss += __shfl_xor(ss, o);
;         const float rs = 1.0f / sqrtf(ss * (1.0f / 256.0f) + EPS);
;         const u32x2 gw2 = *((const u32x2*)(proj + (row0 + c) * PROJ_LD + C_GOUT + h * 256) + lane);
;         const float z0 = bflo(gw2.x), z1 = bfhi(gw2.x), z2 = bflo(gw2.y), z3 = bfhi(gw2.y);
;         const float p0 = v[0] * rs * g[0] * (z0 / (1.0f + __expf(-z0))), p1 = v[1] * rs * g[1] * (z1 / (1.0f + __expf(-z1)));
;         const float p2 = v[2] * rs * g[2] * (z2 / (1.0f + __expf(-z2))), p3 = v[3] * rs * g[3] * (z3 / (1.0f + __expf(-z3)));
;         u32x2 w; w.x = cvt_pk_bf16(p0, p1); w.y = cvt_pk_bf16(p2, p3); *((u32x2*)(omix + (row0 + c) * DM + h * 256) + lane) = w; }
; __global__ void __launch_bounds__(NWAVES * 64, 2) fwd(Args args) {
;     ...
;         for (int un = F.vcu; un < 2048; un += F.G) gla::gc_unit(F.lds, un, proj, dSt, gla_norm_g, omix, F.tid, F.wave, F.lane);
	v_add_f32_e32 v15, v15, v22
	v_fmamk_f32 v15, v15, 0x3b800000, v110
	v_mul_f32_e32 v22, 0x4f800000, v15
	v_cmp_gt_f32_e32 vcc, s65, v15
	s_nop 1
	v_cndmask_b32_e32 v15, v15, v22, vcc
	v_sqrt_f32_e32 v22, v15
	s_nop 0
	v_add_u32_e32 v23, -1, v22
	v_fma_f32 v24, -v23, v22, v15
	v_cmp_ge_f32_e64 s[40:41], 0, v24
	v_add_u32_e32 v24, 1, v22
	s_nop 0
	v_cndmask_b32_e64 v23, v22, v23, s[40:41]
	v_fma_f32 v22, -v24, v22, v15
	v_cmp_lt_f32_e64 s[40:41], 0, v22
	s_nop 1
	v_cndmask_b32_e64 v22, v23, v24, s[40:41]
	v_mul_f32_e32 v23, 0x37800000, v22
	v_cndmask_b32_e32 v22, v22, v23, vcc
	v_cmp_class_f32_e32 vcc, v15, v111
	s_nop 1
	v_cndmask_b32_e32 v15, v22, v15, vcc
	v_div_scale_f32 v22, s[40:41], v15, v15, 1.0
	v_rcp_f32_e32 v23, v22
	s_nop 0
	v_fma_f32 v24, -v22, v23, 1.0
	v_fmac_f32_e32 v23, v24, v23
	v_div_scale_f32 v24, vcc, 1.0, v15, 1.0
	v_mul_f32_e32 v25, v24, v23
	v_fma_f32 v26, -v22, v25, v24
	v_fmac_f32_e32 v25, v26, v23
	v_fma_f32 v22, -v22, v25, v24
	v_div_fmas_f32 v22, v22, v23, v25
	v_mov_b32_e32 v20, v138
	v_mov_b32_e32 v21, v139
	v_lshlrev_b32_e32 v23, 16, v20
	v_mul_f32_e32 v24, 0xbfb8aa3b, v23
	v_exp_f32_e32 v24, v24
	v_and_b32_e32 v20, 0xffff0000, v20
	v_div_fixup_f32 v15, v22, v15, 1.0
	v_mul_f32_e32 v16, v16, v15
	v_add_f32_e32 v24, 1.0, v24
	v_div_scale_f32 v25, s[40:41], v24, v24, v23
	v_rcp_f32_e32 v26, v25
	v_mul_f32_e32 v16, v2, v16
	v_lshlrev_b32_e32 v22, 16, v21
	v_mul_f32_e32 v17, v17, v15
	v_fma_f32 v27, -v25, v26, 1.0
	v_fmac_f32_e32 v26, v27, v26
	v_div_scale_f32 v27, vcc, v23, v24, v23
	v_mul_f32_e32 v28, v27, v26
	v_fma_f32 v29, -v25, v28, v27
	v_fmac_f32_e32 v28, v29, v26
	v_fma_f32 v25, -v25, v28, v27
	v_mul_f32_e32 v27, 0xbfb8aa3b, v20
	v_exp_f32_e32 v27, v27
	v_div_fmas_f32 v25, v25, v26, v28
	v_div_fixup_f32 v23, v25, v24, v23
	v_mul_f32_e32 v16, v23, v16
	v_add_f32_e32 v24, 1.0, v27
	v_div_scale_f32 v25, s[40:41], v24, v24, v20
	v_rcp_f32_e32 v26, v25
	v_mul_f32_e32 v17, v3, v17
	v_and_b32_e32 v21, 0xffff0000, v21
	v_mul_f32_e32 v18, v18, v15
	v_fma_f32 v23, -v25, v26, 1.0
	v_fmac_f32_e32 v26, v23, v26
	v_div_scale_f32 v23, vcc, v20, v24, v20
	v_mul_f32_e32 v27, v23, v26
	v_fma_f32 v28, -v25, v27, v23
	v_fmac_f32_e32 v27, v28, v26
	v_fma_f32 v23, -v25, v27, v23
	v_mul_f32_e32 v25, 0xbfb8aa3b, v22
	v_exp_f32_e32 v25, v25
	v_div_fmas_f32 v23, v23, v26, v27
	v_div_fixup_f32 v20, v23, v24, v20
	v_mul_f32_e32 v17, v20, v17
	v_add_f32_e32 v23, 1.0, v25
	v_div_scale_f32 v24, s[40:41], v23, v23, v22
	v_rcp_f32_e32 v25, v24
	v_mul_f32_e32 v15, v19, v15
	v_mul_f32_e32 v18, v4, v18
	v_mul_f32_e32 v15, v5, v15
	v_fma_f32 v20, -v24, v25, 1.0
	v_fmac_f32_e32 v25, v20, v25
	v_div_scale_f32 v20, vcc, v22, v23, v22
	v_mul_f32_e32 v26, v20, v25
	v_fma_f32 v27, -v24, v26, v20
	v_fmac_f32_e32 v26, v27, v25
	v_fma_f32 v20, -v24, v26, v20
	v_mul_f32_e32 v24, 0xbfb8aa3b, v21
	v_exp_f32_e32 v24, v24
	v_div_fmas_f32 v20, v20, v25, v26
	v_div_fixup_f32 v20, v20, v23, v22
	v_mul_f32_e32 v18, v20, v18
	v_add_f32_e32 v22, 1.0, v24
	v_div_scale_f32 v23, s[40:41], v22, v22, v21
	v_rcp_f32_e32 v24, v23
	s_lshl_b64 s[40:41], s[50:51], 13
	s_add_u32 s48, s48, s60
	s_addc_u32 s49, s49, 0
	v_fma_f32 v19, -v23, v24, 1.0
	v_fmac_f32_e32 v24, v19, v24
	v_div_scale_f32 v19, vcc, v21, v22, v21
	v_mul_f32_e32 v20, v19, v24
	v_fma_f32 v25, -v23, v20, v19
	v_fmac_f32_e32 v20, v25, v24
	v_fma_f32 v19, -v23, v20, v19
	v_div_fmas_f32 v19, v19, v24, v20
	v_div_fixup_f32 v19, v19, v22, v21
	v_mul_f32_e32 v15, v19, v15
	v_cvt_pk_bf16_f32 v16, v16, v17
	v_cvt_pk_bf16_f32 v17, v18, v15
	v_lshl_add_u64 v[18:19], v[6:7], 0, s[40:41]
	s_mul_i32 s40, s49, 0x3000
	s_mul_hi_u32 s41, s48, 0x3000
	s_add_i32 s41, s41, s40
	s_mul_i32 s40, s48, 0x3000
	s_add_u32 s40, s90, s40
	s_addc_u32 s41, s91, s41
	s_add_u32 s40, s40, s38
	s_addc_u32 s41, s41, 0
	global_store_dwordx2 v[18:19], v[16:17], off
	v_lshl_add_u64 v[18:19], s[40:41], 0, v[78:79]
	v_add_co_u32_e32 v18, vcc, s66, v18
	ds_read_b128 v[14:17], v14 offset:10336
	s_nop 0
	v_addc_co_u32_e32 v19, vcc, 0, v19, vcc
	s_add_i32 s94, s94, s88
	s_waitcnt lgkmcnt(0)
	v_mul_f32_e32 v20, v15, v15
	v_mul_f32_e32 v21, v17, v17
	v_fmac_f32_e32 v20, v14, v14
	v_fmac_f32_e32 v21, v16, v16
	v_add_f32_e32 v20, v20, v21
	ds_bpermute_b32 v8, v8, v20
	s_add_i32 s61, s61, s62
	s_waitcnt lgkmcnt(0)
	v_add_f32_e32 v8, v20, v8
	ds_bpermute_b32 v9, v9, v8
	s_waitcnt lgkmcnt(0)
	v_add_f32_e32 v8, v8, v9
	ds_bpermute_b32 v9, v10, v8
	s_waitcnt lgkmcnt(0)
	v_add_f32_e32 v8, v8, v9
	ds_bpermute_b32 v9, v11, v8
	s_waitcnt lgkmcnt(0)
	v_add_f32_e32 v8, v8, v9
	ds_bpermute_b32 v9, v12, v8
	s_waitcnt lgkmcnt(0)
	v_add_f32_e32 v8, v8, v9
	ds_bpermute_b32 v9, v13, v8
	s_waitcnt lgkmcnt(0)
; #define LAS __attribute__((address_space(3)))
; __device__ __forceinline__ unsigned cvt_pk_bf16(float lo, float hi) { unsigned r; asm volatile("v_cvt_pk_bf16_f32 %0, %1, %2" : "=v"(r) : "v"(lo), "v"(hi)); return r; }
; __device__ __forceinline__ float bflo(unsigned w) { return __uint_as_float(w << 16); }
; __device__ __forceinline__ float bfhi(unsigned w) { return __uint_as_float(w & 0xffff0000u); }
; __device__ __forceinline__ void gc_unit(LAS unsigned char* lds, int unit, const bf16_t* proj, const bf16_t* dSt, const float* gnorm, bf16_t* omix, int tid, int wave, int lane) {
;     ...
;     for (int rr = 0; rr < 8; ++rr) { const int c = 8 * wave + rr; const f32x4 v = *(const LAS f32x4*)(lds + L_OT + c * 1040 + lane * 16);
;         float ss = (v[0] * v[0] + v[1] * v[1]) + (v[2] * v[2] + v[3] * v[3]);
; #pragma unroll
;         for (int o = 1; o < 64; o <<= 1) ss += __shfl_xor(ss, o);
;         const float rs = 1.0f / sqrtf(ss * (1.0f / 256.0f) + EPS);
;         const u32x2 gw2 = *((const u32x2*)(proj + (row0 + c) * PROJ_LD + C_GOUT + h * 256) + lane);
;         const float z0 = bflo(gw2.x), z1 = bfhi(gw2.x), z2 = bflo(gw2.y), z3 = bfhi(gw2.y);
;         const float p0 = v[0] * rs * g[0] * (z0 / (1.0f + __expf(-z0))), p1 = v[1] * rs * g[1] * (z1 / (1.0f + __expf(-z1)));
;         const float p2 = v[2] * rs * g[2] * (z2 / (1.0f + __expf(-z2))), p3 = v[3] * rs * g[3] * (z3 / (1.0f + __expf(-z3)));
;         u32x2 w; w.x = cvt_pk_bf16(p0, p1); w.y = cvt_pk_bf16(p2, p3); *((u32x2*)(omix + (row0 + c) * DM + h * 256) + lane) = w; }
;     __syncthreads();
	v_add_f32_e32 v8, v8, v9
	v_fmamk_f32 v8, v8, 0x3b800000, v110
	v_mul_f32_e32 v9, 0x4f800000, v8
	v_cmp_gt_f32_e32 vcc, s65, v8
	s_nop 1
	v_cndmask_b32_e32 v8, v8, v9, vcc
	v_sqrt_f32_e32 v9, v8
	s_nop 0
	v_add_u32_e32 v10, -1, v9
	v_fma_f32 v11, -v10, v9, v8
	v_cmp_ge_f32_e64 s[40:41], 0, v11
	v_add_u32_e32 v11, 1, v9
	s_nop 0
	v_cndmask_b32_e64 v10, v9, v10, s[40:41]
	v_fma_f32 v9, -v11, v9, v8
	v_cmp_lt_f32_e64 s[40:41], 0, v9
	s_nop 1
	v_cndmask_b32_e64 v9, v10, v11, s[40:41]
	v_mul_f32_e32 v10, 0x37800000, v9
	v_cndmask_b32_e32 v9, v9, v10, vcc
	v_cmp_class_f32_e32 vcc, v8, v111
	s_nop 1
	v_cndmask_b32_e32 v8, v9, v8, vcc
	v_div_scale_f32 v9, s[40:41], v8, v8, 1.0
	v_rcp_f32_e32 v10, v9
	s_nop 0
	v_fma_f32 v11, -v9, v10, 1.0
	v_fmac_f32_e32 v10, v11, v10
	v_div_scale_f32 v11, vcc, 1.0, v8, 1.0
	v_mul_f32_e32 v12, v11, v10
	v_fma_f32 v13, -v9, v12, v11
	v_fmac_f32_e32 v12, v13, v10
	v_fma_f32 v9, -v9, v12, v11
	v_div_fmas_f32 v9, v9, v10, v12
	v_mov_b32_e32 v18, v140
	v_mov_b32_e32 v19, v141
	v_lshlrev_b32_e32 v10, 16, v18
	v_mul_f32_e32 v11, 0xbfb8aa3b, v10
	v_exp_f32_e32 v11, v11
	v_div_fixup_f32 v8, v9, v8, 1.0
	v_and_b32_e32 v9, 0xffff0000, v18
	v_mul_f32_e32 v14, v14, v8
	v_add_f32_e32 v11, 1.0, v11
	v_div_scale_f32 v13, s[40:41], v11, v11, v10
	v_rcp_f32_e32 v18, v13
	v_mul_f32_e32 v2, v2, v14
	v_lshlrev_b32_e32 v12, 16, v19
	v_and_b32_e32 v19, 0xffff0000, v19
	v_fma_f32 v14, -v13, v18, 1.0
	v_fmac_f32_e32 v18, v14, v18
	v_div_scale_f32 v14, vcc, v10, v11, v10
	v_mul_f32_e32 v20, v14, v18
	v_fma_f32 v21, -v13, v20, v14
	v_fmac_f32_e32 v20, v21, v18
	v_fma_f32 v13, -v13, v20, v14
	v_mul_f32_e32 v14, 0xbfb8aa3b, v9
	v_exp_f32_e32 v14, v14
	v_div_fmas_f32 v13, v13, v18, v20
	v_div_fixup_f32 v10, v13, v11, v10
	v_mul_f32_e32 v2, v10, v2
	v_add_f32_e32 v11, 1.0, v14
	v_div_scale_f32 v13, s[40:41], v11, v11, v9
	v_rcp_f32_e32 v14, v13
	v_mul_f32_e32 v10, v15, v8
	v_mul_f32_e32 v3, v3, v10
	v_fma_f32 v10, -v13, v14, 1.0
	v_fmac_f32_e32 v14, v10, v14
	v_div_scale_f32 v10, vcc, v9, v11, v9
	v_mul_f32_e32 v15, v10, v14
	v_fma_f32 v18, -v13, v15, v10
	v_fmac_f32_e32 v15, v18, v14
	v_fma_f32 v10, -v13, v15, v10
	v_mul_f32_e32 v13, 0xbfb8aa3b, v12
	v_exp_f32_e32 v13, v13
	v_div_fmas_f32 v10, v10, v14, v15
	v_div_fixup_f32 v9, v10, v11, v9
	v_mul_f32_e32 v3, v9, v3
	v_add_f32_e32 v10, 1.0, v13
	v_div_scale_f32 v11, s[40:41], v10, v10, v12
	v_rcp_f32_e32 v13, v11
	v_mul_f32_e32 v9, v16, v8
	v_mul_f32_e32 v4, v4, v9
	v_mul_f32_e32 v8, v17, v8
	v_fma_f32 v9, -v11, v13, 1.0
	v_fmac_f32_e32 v13, v9, v13
	v_div_scale_f32 v9, vcc, v12, v10, v12
	v_mul_f32_e32 v14, v9, v13
	v_fma_f32 v15, -v11, v14, v9
	v_fmac_f32_e32 v14, v15, v13
	v_fma_f32 v9, -v11, v14, v9
	v_mul_f32_e32 v11, 0xbfb8aa3b, v19
	v_exp_f32_e32 v11, v11
	v_div_fmas_f32 v9, v9, v13, v14
	v_div_fixup_f32 v9, v9, v10, v12
	v_mul_f32_e32 v5, v5, v8
	v_add_f32_e32 v10, 1.0, v11
	v_div_scale_f32 v11, s[40:41], v10, v10, v19
	v_rcp_f32_e32 v12, v11
	v_mul_f32_e32 v4, v9, v4
	s_lshl_b64 s[40:41], s[48:49], 13
	v_cvt_pk_bf16_f32 v2, v2, v3
	v_fma_f32 v8, -v11, v12, 1.0
	v_fmac_f32_e32 v12, v8, v12
	v_div_scale_f32 v8, vcc, v19, v10, v19
	v_mul_f32_e32 v9, v8, v12
	v_fma_f32 v13, -v11, v9, v8
	v_fmac_f32_e32 v9, v13, v12
	v_fma_f32 v8, -v11, v9, v8
	v_div_fmas_f32 v8, v8, v12, v9
	v_div_fixup_f32 v8, v8, v10, v19
	v_mul_f32_e32 v5, v8, v5
	v_cvt_pk_bf16_f32 v3, v4, v5
	v_lshl_add_u64 v[4:5], v[6:7], 0, s[40:41]
	s_cmpk_lt_i32 s94, 0x800
	global_store_dwordx2 v[4:5], v[2:3], off
	s_barrier
	s_cbranch_scc0 .LBB0_1022
; #define LAS __attribute__((address_space(3)))
; __device__ __forceinline__ int crow(int r, int hi) { return (r & 3) + 8 * (r >> 2) + 4 * hi; }
; __device__ __forceinline__ int crow(int r, int hi) { return (r & 3) + 8 * (r >> 2) + 4 * hi; }
; __device__ __forceinline__ unsigned short f2bf1(float x) { return (unsigned short)(cvt_pk_bf16(x, 0.f) & 0xffffu); }
; __device__ __forceinline__ void gc_unit(LAS unsigned char* lds, int unit, const bf16_t* proj, const bf16_t* dSt, const float* gnorm, bf16_t* omix, int tid, int wave, int lane) {
;     const int n = unit & 63, bh = unit >> 6, b = bh >> 3, h = bh & 7;
;     const size_t row0 = (size_t)b * SEQ + n * 64;
;     bf16x8 sfr[8];
;     { const bf16_t* sp = dSt + ((size_t)unit * 256 + 32 * wave + (lane & 31)) * 128 + (lane >> 5) * 8;
; #pragma unroll
;       for (int ks = 0; ks < 8; ++ks) sfr[ks] = *(const bf16x8*)(sp + ks * 16); }
;     { const int t = tid >> 3, c0 = (tid & 7) * 16; const bf16_t* qp = proj + (row0 + t) * PROJ_LD + C_GQ + h * 128 + c0;
;       const u32x4 q0 = *(const u32x4*)qp, q1 = *(const u32x4*)(qp + 8), k0 = *(const u32x4*)(qp + (C_GK - C_GQ)), k1 = *(const u32x4*)(qp + (C_GK - C_GQ) + 8);
;       u32x4 vr[4]; load_v(vr, proj + row0 * PROJ_LD + C_GV + h * 256, tid);
;       *(LAS u32x4*)(lds + L_QD + t * 272 + c0 * 2) = q0; *(LAS u32x4*)(lds + L_QD + t * 272 + c0 * 2 + 16) = q1;
;       *(LAS u32x4*)(lds + L_KI + t * 272 + c0 * 2) = k0; *(LAS u32x4*)(lds + L_KI + t * 272 + c0 * 2 + 16) = k1;
;       store_v(lds, L_VT, vr, tid); }
;     __syncthreads();
;     const int r = lane & 31, hh = lane >> 5;
;     if (wave < 4) { const int ct = wave & 1, st = wave >> 1; f32x16 acc = {};
; #pragma unroll
;         for (int ks = 0; ks < 8; ++ks) { const bf16x8 a = *(const LAS bf16x8*)(lds + L_QD + (ct * 32 + r) * 272 + ks * 32 + hh * 16), bb = *(const LAS bf16x8*)(lds + L_KI + (st * 32 + r) * 272 + ks * 32 + hh * 16);
;             acc = __builtin_amdgcn_mfma_f32_32x32x16_bf16(a, bb, acc, 0, 0, 0); }
; #pragma unroll
;         for (int i = 0; i < 16; ++i) { const int c = ct * 32 + crow(i, hh), s2 = st * 32 + r; const float val = (s2 <= c) ? acc[i] : 0.f;
;             *(LAS unsigned short*)(lds + L_AT + c * 144 + s2 * 2) = f2bf1(val); } }
;     __syncthreads();
.LBB0_1009:
	s_ashr_i32 s40, s94, 9
	s_ashr_i32 s41, s40, 31
	s_and_b32 s38, s61, 0xfc0
	s_lshl_b64 s[48:49], s[40:41], 12
	s_or_b32 s48, s48, s38
	v_or_b32_e32 v2, s48, v80
	v_mad_u64_u32 v[2:3], s[40:41], v2, s63, v[88:89]
	s_bfe_u32 s50, s94, 0x30006
	s_mul_i32 s40, s49, 0x3000
	s_mul_hi_u32 s41, s48, 0x3000
	s_lshl_b32 s38, s50, 8
	s_add_i32 s41, s41, s40
	s_mul_i32 s40, s48, 0x3000
	s_add_u32 s40, s90, s40
	v_mad_i32_i24 v3, s49, v99, v3
	s_addc_u32 s41, s91, s41
	s_lshl_b32 s50, s50, 9
	v_lshl_add_u64 v[2:3], v[2:3], 0, s[38:39]
	s_add_u32 s40, s40, s50
	v_lshl_add_u64 v[14:15], v[2:3], 0, v[90:91]
	s_addc_u32 s41, s41, 0
	global_load_dwordx4 v[38:41], v[84:85], off offset:-224
	global_load_dwordx4 v[34:37], v[84:85], off offset:-192
	global_load_dwordx4 v[2:5], v[14:15], off offset:16
	global_load_dwordx4 v[6:9], v[14:15], off
	global_load_dwordx4 v[10:13], v[14:15], off offset:2064
	s_nop 0
	global_load_dwordx4 v[14:17], v[14:15], off offset:2048
	v_lshl_add_u64 v[18:19], s[40:41], 0, v[92:93]
	v_lshl_add_u64 v[18:19], v[18:19], 0, v[94:95]
	v_lshl_add_u64 v[30:31], v[18:19], 0, s[46:47]
	v_add_co_u32_e32 v18, vcc, s64, v18
	s_nop 1
	v_addc_co_u32_e32 v19, vcc, 0, v19, vcc
	global_load_dwordx4 v[18:21], v[18:19], off
	s_nop 0
	global_load_dwordx4 v[22:25], v[30:31], off offset:32
	global_load_dwordx4 v[26:29], v[30:31], off offset:16
	global_load_dwordx4 v[62:65], v[84:85], off offset:-160
	global_load_dwordx4 v[58:61], v[84:85], off offset:-128
	s_nop 0
	global_load_dwordx4 v[30:33], v[30:31], off offset:48
	s_nop 0
	global_load_dwordx4 v[54:57], v[84:85], off offset:-96
	global_load_dwordx4 v[50:53], v[84:85], off offset:-64
	global_load_dwordx4 v[46:49], v[84:85], off offset:-32
	global_load_dwordx4 v[42:45], v[84:85], off
	s_andn2_b64 vcc, exec, s[42:43]
	s_waitcnt vmcnt(0)
	ds_write_b128 v100, v[6:9] offset:4096
	ds_write_b128 v100, v[2:5] offset:4112
	ds_write_b128 v100, v[14:17] offset:21504
	ds_write_b128 v100, v[10:13] offset:21520
	ds_write_b128 v101, v[18:21] offset:38912
	ds_write_b128 v101, v[26:29] offset:38928
	ds_write_b128 v101, v[22:25] offset:38944
	ds_write_b128 v101, v[30:33] offset:38960
	s_waitcnt lgkmcnt(0)
	s_barrier
	s_cbranch_vccnz .LBB0_1011
	ds_read_b128 v[2:5], v102 offset:4096
	ds_read_b128 v[6:9], v103 offset:21504
	ds_read_b128 v[18:21], v102 offset:4128
	ds_read_b128 v[22:25], v103 offset:21536
	s_waitcnt lgkmcnt(2)
	v_mfma_f32_32x32x16_bf16 v[2:17], v[2:5], v[6:9], 0
	s_waitcnt lgkmcnt(0)
	v_mfma_f32_32x32x16_bf16 v[2:17], v[18:21], v[22:25], v[2:17]
	ds_read_b128 v[18:21], v102 offset:4160
	ds_read_b128 v[22:25], v103 offset:21568
	ds_read_b128 v[26:29], v102 offset:4192
	ds_read_b128 v[30:33], v103 offset:21600
	s_waitcnt lgkmcnt(2)
	v_mfma_f32_32x32x16_bf16 v[2:17], v[18:21], v[22:25], v[2:17]
	s_waitcnt lgkmcnt(0)
	v_mfma_f32_32x32x16_bf16 v[2:17], v[26:29], v[30:33], v[2:17]
	ds_read_b128 v[18:21], v102 offset:4224
	ds_read_b128 v[22:25], v103 offset:21632
	ds_read_b128 v[26:29], v102 offset:4256
	ds_read_b128 v[30:33], v103 offset:21664
	s_waitcnt lgkmcnt(2)
	v_mfma_f32_32x32x16_bf16 v[2:17], v[18:21], v[22:25], v[2:17]
	s_waitcnt lgkmcnt(0)
	v_mfma_f32_32x32x16_bf16 v[2:17], v[26:29], v[30:33], v[2:17]
	ds_read_b128 v[18:21], v102 offset:4288
	ds_read_b128 v[22:25], v103 offset:21696
	ds_read_b128 v[26:29], v102 offset:4320
	ds_read_b128 v[30:33], v103 offset:21728
	s_waitcnt lgkmcnt(2)
	v_mfma_f32_32x32x16_bf16 v[2:17], v[18:21], v[22:25], v[2:17]
	s_waitcnt lgkmcnt(0)
	v_mfma_f32_32x32x16_bf16 v[2:17], v[26:29], v[30:33], v[2:17]
	s_nop 11
	v_cndmask_b32_e64 v2, v2, 0, s[4:5]
	v_cvt_pk_bf16_f32 v2, v2, v79
	v_cndmask_b32_e64 v3, v3, 0, s[6:7]
	ds_write_b16 v104, v2
	v_cvt_pk_bf16_f32 v2, v3, v79
	v_cndmask_b32_e64 v4, v4, 0, s[8:9]
	ds_write_b16 v104, v2 offset:144
	v_cvt_pk_bf16_f32 v2, v4, v79
	v_cndmask_b32_e64 v5, v5, 0, s[10:11]
	ds_write_b16 v104, v2 offset:288
	v_cvt_pk_bf16_f32 v2, v5, v79
	v_cndmask_b32_e64 v6, v6, 0, s[12:13]
	ds_write_b16 v104, v2 offset:432
	v_cvt_pk_bf16_f32 v2, v6, v79
	v_cndmask_b32_e64 v7, v7, 0, s[14:15]
	ds_write_b16 v104, v2 offset:1152
	v_cvt_pk_bf16_f32 v2, v7, v79
	v_cndmask_b32_e64 v8, v8, 0, s[16:17]
	ds_write_b16 v104, v2 offset:1296
	v_cvt_pk_bf16_f32 v2, v8, v79
	v_cndmask_b32_e64 v9, v9, 0, s[18:19]
	ds_write_b16 v104, v2 offset:1440
	v_cvt_pk_bf16_f32 v2, v9, v79
	v_cndmask_b32_e64 v10, v10, 0, s[20:21]
	ds_write_b16 v104, v2 offset:1584
	v_cvt_pk_bf16_f32 v2, v10, v79
	v_cndmask_b32_e64 v11, v11, 0, s[22:23]
	ds_write_b16 v104, v2 offset:2304
	v_cvt_pk_bf16_f32 v2, v11, v79
	v_cndmask_b32_e64 v12, v12, 0, s[24:25]
	ds_write_b16 v104, v2 offset:2448
	v_cvt_pk_bf16_f32 v2, v12, v79
	v_cndmask_b32_e64 v13, v13, 0, s[26:27]
	ds_write_b16 v104, v2 offset:2592
	v_cvt_pk_bf16_f32 v2, v13, v79
	v_cndmask_b32_e64 v14, v14, 0, s[28:29]
	ds_write_b16 v104, v2 offset:2736
	v_cvt_pk_bf16_f32 v2, v14, v79
	v_cndmask_b32_e64 v15, v15, 0, s[30:31]
	ds_write_b16 v104, v2 offset:3456
	v_cvt_pk_bf16_f32 v2, v15, v79
	v_cndmask_b32_e64 v16, v16, 0, s[34:35]
	ds_write_b16 v104, v2 offset:3600
	v_cvt_pk_bf16_f32 v2, v16, v79
	v_cndmask_b32_e64 v17, v17, 0, s[36:37]
	ds_write_b16 v104, v2 offset:3744
	v_cvt_pk_bf16_f32 v2, v17, v79
	ds_write_b16 v104, v2 offset:3888

; __global__ void __launch_bounds__(NWAVES * 64, 2) fwd(Args args) {
;     extern __shared__ __attribute__((aligned(16))) unsigned char lds[];
	.amdhsa_kernel _Z3fwd4Args
		.amdhsa_group_segment_fixed_size 0
		.amdhsa_private_segment_fixed_size 0
		.amdhsa_kernarg_size 424
		.amdhsa_user_sgpr_count 2
		.amdhsa_user_sgpr_dispatch_ptr 0
		.amdhsa_user_sgpr_queue_ptr 0
		.amdhsa_user_sgpr_kernarg_segment_ptr 1
		.amdhsa_user_sgpr_dispatch_id 0
		.amdhsa_user_sgpr_kernarg_preload_length 0
		.amdhsa_user_sgpr_kernarg_preload_offset 0
		.amdhsa_user_sgpr_private_segment_size 0
		.amdhsa_uses_dynamic_stack 0
		.amdhsa_enable_private_segment 0
		.amdhsa_system_sgpr_workgroup_id_x 1
		.amdhsa_system_sgpr_workgroup_id_y 0
		.amdhsa_system_sgpr_workgroup_id_z 0
		.amdhsa_system_sgpr_workgroup_info 0
		.amdhsa_system_vgpr_workitem_id 0
		.amdhsa_next_free_vgpr 255
		.amdhsa_next_free_sgpr 102
		.amdhsa_accum_offset 256
		.amdhsa_reserve_vcc 1
		.amdhsa_float_round_mode_32 0
		.amdhsa_float_round_mode_16_64 0
		.amdhsa_float_denorm_mode_32 3
		.amdhsa_float_denorm_mode_16_64 3
		.amdhsa_dx10_clamp 1
		.amdhsa_ieee_mode 1
		.amdhsa_fp16_overflow 0
		.amdhsa_tg_split 0
		.amdhsa_exception_fp_ieee_invalid_op 0
		.amdhsa_exception_fp_denorm_src 0
		.amdhsa_exception_fp_ieee_div_zero 0
		.amdhsa_exception_fp_ieee_overflow 0
		.amdhsa_exception_fp_ieee_underflow 0
		.amdhsa_exception_fp_ieee_inexact 0
		.amdhsa_exception_int_div_zero 0
	.end_amdhsa_kernel

; __global__ void __launch_bounds__(NWAVES * 64, 2) fwd(Args args) {
amdhsa.kernels:
  - .agpr_count:     0
    .args:
      - .offset:         0
        .size:           168
        .value_kind:     by_value
      - .offset:         168
        .size:           4
        .value_kind:     hidden_block_count_x
      - .offset:         172
        .size:           4
        .value_kind:     hidden_block_count_y
      - .offset:         176
        .size:           4
        .value_kind:     hidden_block_count_z
      - .offset:         180
        .size:           2
        .value_kind:     hidden_group_size_x
      - .offset:         182
        .size:           2
        .value_kind:     hidden_group_size_y
      - .offset:         184
        .size:           2
        .value_kind:     hidden_group_size_z
      - .offset:         186
        .size:           2
        .value_kind:     hidden_remainder_x
      - .offset:         188
        .size:           2
        .value_kind:     hidden_remainder_y
      - .offset:         190
        .size:           2
        .value_kind:     hidden_remainder_z
      - .offset:         208
        .size:           8
        .value_kind:     hidden_global_offset_x
      - .offset:         216
        .size:           8
        .value_kind:     hidden_global_offset_y
      - .offset:         224
        .size:           8
        .value_kind:     hidden_global_offset_z
      - .offset:         232
        .size:           2
        .value_kind:     hidden_grid_dims
      - .offset:         288
        .size:           4
        .value_kind:     hidden_dynamic_lds_size
    .group_segment_fixed_size: 0
    .kernarg_segment_align: 8
    .kernarg_segment_size: 424
    .language:       OpenCL C
    .language_version:
      - 2
      - 0
    .max_flat_workgroup_size: 512
    .name:           _Z3fwd4Args
    .private_segment_fixed_size: 0
    .sgpr_count:     108
    .sgpr_spill_count: 62
    .symbol:         _Z3fwd4Args.kd
    .uniform_work_group_size: 1
    .uses_dynamic_stack: false
    .vgpr_count:     255
    .vgpr_spill_count: 0
    .wavefront_size: 64
